# conv loop: second sub-item's FMA block duplicated for the path with the next item's 46 prefetch loads in flight (counted waits +46), deferred ticket atomic waited with vmcnt(46) instead of 0; on top o
# speedup vs baseline: 1.0021x; 1.0021x over previous
.Lconv_pf_join:
	v_lshlrev_b32_e32 v168, 16, v80
	v_and_b32_e32 v169, 0xffff0000, v80
	v_mov_b32_e32 v80, s20
	v_pk_fma_f32 v[166:167], v[70:71], v[168:169], v[166:167]
	ds_write2st64_b64 v102, v[150:151], v[148:149] offset0:64 offset1:68
	ds_write2st64_b64 v102, v[152:153], v[146:147] offset0:72 offset1:76
	ds_write2st64_b64 v102, v[154:155], v[144:145] offset0:80 offset1:84
	ds_write2st64_b64 v102, v[156:157], v[142:143] offset0:88 offset1:92
	ds_write2st64_b64 v102, v[158:159], v[160:161] offset0:96 offset1:100
	ds_write2st64_b64 v102, v[140:141], v[138:139] offset0:104 offset1:108
	ds_write2st64_b64 v102, v[162:163], v[136:137] offset0:112 offset1:116
	ds_write2st64_b64 v102, v[164:165], v[166:167] offset0:120 offset1:124
	s_and_saveexec_b64 s[98:99], s[4:5]
	s_cbranch_execz .Lconv_tk
	s_waitcnt vmcnt(46)
	v_mov_b32_e32 v231, s20
	s_nop 0
	ds_write_b32 v231, v230

.LBB0_496:
	s_or_b64 exec, exec, s[98:99]
	s_lshl_b32 s8, s29, 6
	s_add_i32 s0, s8, s3
	s_ashr_i32 s1, s0, 13
	s_mulk_i32 s1, 0x2040
	s_and_b32 s0, s0, 0x1fe0
	s_add_i32 s0, s0, s1
	s_add_i32 s0, s0, 50
	s_ashr_i32 s1, s0, 31
	s_lshl_b64 s[0:1], s[0:1], 10
	v_lshl_add_u64 v[136:137], v[82:83], 0, s[0:1]
	v_add_co_u32_e32 v138, vcc, 0x1000, v136
	s_waitcnt vmcnt(5)
	v_lshlrev_b32_e32 v184, 16, v105
	v_addc_co_u32_e32 v139, vcc, 0, v137, vcc
	global_load_dword v179, v[136:137], off
	global_load_dword v178, v[136:137], off offset:1024
	global_load_dword v177, v[136:137], off offset:2048
	global_load_dword v176, v[136:137], off offset:3072
	global_load_dword v175, v[138:139], off
	global_load_dword v174, v[138:139], off offset:1024
	global_load_dword v173, v[138:139], off offset:2048
	global_load_dword v171, v[138:139], off offset:3072
	v_add_co_u32_e32 v138, vcc, 0x2000, v136
	v_and_b32_e32 v185, 0xffff0000, v105
	s_nop 0
	v_addc_co_u32_e32 v139, vcc, 0, v137, vcc
	v_add_co_u32_e32 v140, vcc, 0x3000, v136
	s_waitcnt vmcnt(12)
	v_lshlrev_b32_e32 v186, 16, v106
	v_addc_co_u32_e32 v141, vcc, 0, v137, vcc
	global_load_dword v172, v[138:139], off
	global_load_dword v170, v[138:139], off offset:1024
	global_load_dword v169, v[138:139], off offset:2048
	global_load_dword v168, v[138:139], off offset:3072
	global_load_dword v167, v[140:141], off
	global_load_dword v166, v[140:141], off offset:1024
	global_load_dword v165, v[140:141], off offset:2048
	global_load_dword v164, v[140:141], off offset:3072
	v_add_co_u32_e32 v138, vcc, 0x4000, v136
	v_and_b32_e32 v187, 0xffff0000, v106
	s_nop 0
	v_addc_co_u32_e32 v139, vcc, 0, v137, vcc
	v_add_co_u32_e32 v140, vcc, 0x5000, v136
	s_waitcnt vmcnt(19)
	v_lshlrev_b32_e32 v188, 16, v107
	v_addc_co_u32_e32 v141, vcc, 0, v137, vcc
	global_load_dword v163, v[138:139], off
	global_load_dword v162, v[138:139], off offset:1024
	global_load_dword v161, v[138:139], off offset:2048
	global_load_dword v160, v[138:139], off offset:3072
	global_load_dword v159, v[140:141], off
	global_load_dword v158, v[140:141], off offset:1024
	global_load_dword v157, v[140:141], off offset:2048
	global_load_dword v156, v[140:141], off offset:3072
	v_add_co_u32_e32 v138, vcc, 0x6000, v136
	v_and_b32_e32 v189, 0xffff0000, v107
	s_nop 0
	v_addc_co_u32_e32 v139, vcc, 0, v137, vcc
	v_add_co_u32_e32 v140, vcc, 0x7000, v136
	v_lshlrev_b32_e32 v190, 16, v85
	s_nop 0
	v_addc_co_u32_e32 v141, vcc, 0, v137, vcc
	global_load_dword v155, v[138:139], off
	global_load_dword v154, v[138:139], off offset:1024
	global_load_dword v153, v[138:139], off offset:2048
	global_load_dword v152, v[138:139], off offset:3072
	global_load_dword v151, v[140:141], off
	global_load_dword v150, v[140:141], off offset:1024
	global_load_dword v149, v[140:141], off offset:2048
	global_load_dword v148, v[140:141], off offset:3072
	v_add_co_u32_e32 v138, vcc, 0x8000, v136
	v_and_b32_e32 v191, 0xffff0000, v85
	s_nop 0
	v_addc_co_u32_e32 v139, vcc, 0, v137, vcc
	v_add_co_u32_e32 v180, vcc, 0x9000, v136
	v_lshlrev_b32_e32 v192, 16, v86
	s_nop 0
	v_addc_co_u32_e32 v181, vcc, 0, v137, vcc
	global_load_dword v147, v[138:139], off
	global_load_dword v146, v[138:139], off offset:1024
	global_load_dword v145, v[138:139], off offset:2048
	global_load_dword v144, v[138:139], off offset:3072
	global_load_dword v143, v[180:181], off
	global_load_dword v142, v[180:181], off offset:1024
	global_load_dword v141, v[180:181], off offset:2048
	s_nop 0
	global_load_dword v139, v[180:181], off offset:3072
	v_add_co_u32_e32 v180, vcc, 0xa000, v136
	v_and_b32_e32 v193, 0xffff0000, v86
	s_nop 0
	v_addc_co_u32_e32 v181, vcc, 0, v137, vcc
	v_add_co_u32_e32 v182, vcc, 0xb000, v136
	v_lshlrev_b32_e32 v194, 16, v87
	s_nop 0
	v_addc_co_u32_e32 v183, vcc, 0, v137, vcc
	global_load_dword v140, v[180:181], off
	global_load_dword v138, v[180:181], off offset:1024
	global_load_dword v137, v[180:181], off offset:2048
	global_load_dword v136, v[180:181], off offset:3072
	global_load_dword v135, v[182:183], off
	global_load_dword v80, v[182:183], off offset:1024
	v_lshlrev_b32_e32 v180, 16, v103
	v_and_b32_e32 v181, 0xffff0000, v103
	v_pk_fma_f32 v[180:181], v[72:73], v[180:181], v[78:79]
	v_lshlrev_b32_e32 v182, 16, v104
	v_and_b32_e32 v183, 0xffff0000, v104
	v_pk_fma_f32 v[180:181], v[74:75], v[182:183], v[180:181]
	v_pk_fma_f32 v[182:183], v[72:73], v[182:183], v[78:79]
	v_pk_fma_f32 v[180:181], v[76:77], v[184:185], v[180:181]
	v_pk_fma_f32 v[182:183], v[74:75], v[184:185], v[182:183]
	v_pk_fma_f32 v[184:185], v[72:73], v[184:185], v[78:79]
	v_pk_fma_f32 v[180:181], v[32:33], v[186:187], v[180:181]
	v_pk_fma_f32 v[182:183], v[76:77], v[186:187], v[182:183]
	v_pk_fma_f32 v[184:185], v[74:75], v[186:187], v[184:185]
	v_pk_fma_f32 v[186:187], v[72:73], v[186:187], v[78:79]
	v_pk_fma_f32 v[180:181], v[16:17], v[188:189], v[180:181]
	v_pk_fma_f32 v[182:183], v[32:33], v[188:189], v[182:183]
	v_pk_fma_f32 v[184:185], v[76:77], v[188:189], v[184:185]
	v_pk_fma_f32 v[186:187], v[74:75], v[188:189], v[186:187]
	v_pk_fma_f32 v[188:189], v[72:73], v[188:189], v[78:79]
	v_pk_fma_f32 v[180:181], v[18:19], v[190:191], v[180:181]
	v_pk_fma_f32 v[182:183], v[16:17], v[190:191], v[182:183]
	v_pk_fma_f32 v[184:185], v[32:33], v[190:191], v[184:185]
	v_pk_fma_f32 v[186:187], v[76:77], v[190:191], v[186:187]
	v_pk_fma_f32 v[188:189], v[74:75], v[190:191], v[188:189]
	v_pk_fma_f32 v[190:191], v[72:73], v[190:191], v[78:79]
	v_pk_fma_f32 v[180:181], v[20:21], v[192:193], v[180:181]
	v_pk_fma_f32 v[182:183], v[18:19], v[192:193], v[182:183]
	v_pk_fma_f32 v[184:185], v[16:17], v[192:193], v[184:185]
	v_pk_fma_f32 v[186:187], v[32:33], v[192:193], v[186:187]
	v_pk_fma_f32 v[188:189], v[76:77], v[192:193], v[188:189]
	v_pk_fma_f32 v[190:191], v[74:75], v[192:193], v[190:191]
	v_pk_fma_f32 v[192:193], v[72:73], v[192:193], v[78:79]
	v_and_b32_e32 v195, 0xffff0000, v87
	v_pk_fma_f32 v[180:181], v[34:35], v[194:195], v[180:181]
	v_pk_fma_f32 v[182:183], v[20:21], v[194:195], v[182:183]
	v_pk_fma_f32 v[184:185], v[18:19], v[194:195], v[184:185]
	v_pk_fma_f32 v[186:187], v[16:17], v[194:195], v[186:187]
	v_pk_fma_f32 v[188:189], v[32:33], v[194:195], v[188:189]
	v_pk_fma_f32 v[190:191], v[76:77], v[194:195], v[190:191]
	v_pk_fma_f32 v[192:193], v[74:75], v[194:195], v[192:193]
	v_pk_fma_f32 v[194:195], v[72:73], v[194:195], v[78:79]
	s_waitcnt vmcnt(48)
	v_lshlrev_b32_e32 v196, 16, v114
	v_and_b32_e32 v197, 0xffff0000, v114
	v_pk_fma_f32 v[180:181], v[22:23], v[196:197], v[180:181]
	v_pk_fma_f32 v[182:183], v[34:35], v[196:197], v[182:183]
	v_pk_fma_f32 v[184:185], v[20:21], v[196:197], v[184:185]
	v_pk_fma_f32 v[186:187], v[18:19], v[196:197], v[186:187]
	v_pk_fma_f32 v[188:189], v[16:17], v[196:197], v[188:189]
	v_pk_fma_f32 v[190:191], v[32:33], v[196:197], v[190:191]
	v_pk_fma_f32 v[192:193], v[76:77], v[196:197], v[192:193]
	v_pk_fma_f32 v[194:195], v[74:75], v[196:197], v[194:195]
	v_pk_fma_f32 v[196:197], v[72:73], v[196:197], v[78:79]
	s_waitcnt vmcnt(47)
	v_lshlrev_b32_e32 v198, 16, v115
	v_and_b32_e32 v199, 0xffff0000, v115
	v_pk_fma_f32 v[180:181], v[24:25], v[198:199], v[180:181]
	v_pk_fma_f32 v[182:183], v[22:23], v[198:199], v[182:183]
	v_pk_fma_f32 v[184:185], v[34:35], v[198:199], v[184:185]
	v_pk_fma_f32 v[186:187], v[20:21], v[198:199], v[186:187]
	v_pk_fma_f32 v[188:189], v[18:19], v[198:199], v[188:189]
	v_pk_fma_f32 v[190:191], v[16:17], v[198:199], v[190:191]
	v_pk_fma_f32 v[192:193], v[32:33], v[198:199], v[192:193]
	v_pk_fma_f32 v[194:195], v[76:77], v[198:199], v[194:195]
	v_pk_fma_f32 v[196:197], v[74:75], v[198:199], v[196:197]
	v_pk_fma_f32 v[198:199], v[72:73], v[198:199], v[78:79]
	v_lshlrev_b32_e32 v200, 16, v88
	v_and_b32_e32 v201, 0xffff0000, v88
	v_pk_fma_f32 v[180:181], v[26:27], v[200:201], v[180:181]
	v_pk_fma_f32 v[182:183], v[24:25], v[200:201], v[182:183]
	v_pk_fma_f32 v[184:185], v[22:23], v[200:201], v[184:185]
	v_pk_fma_f32 v[186:187], v[34:35], v[200:201], v[186:187]
	v_pk_fma_f32 v[188:189], v[20:21], v[200:201], v[188:189]
	v_pk_fma_f32 v[190:191], v[18:19], v[200:201], v[190:191]
	v_pk_fma_f32 v[192:193], v[16:17], v[200:201], v[192:193]
	v_pk_fma_f32 v[194:195], v[32:33], v[200:201], v[194:195]
	v_pk_fma_f32 v[196:197], v[76:77], v[200:201], v[196:197]
	v_pk_fma_f32 v[198:199], v[74:75], v[200:201], v[198:199]
	v_pk_fma_f32 v[200:201], v[72:73], v[200:201], v[78:79]
	v_lshlrev_b32_e32 v202, 16, v89
	v_and_b32_e32 v203, 0xffff0000, v89
	v_pk_fma_f32 v[180:181], v[36:37], v[202:203], v[180:181]
	v_pk_fma_f32 v[182:183], v[26:27], v[202:203], v[182:183]
	v_pk_fma_f32 v[184:185], v[24:25], v[202:203], v[184:185]
	v_pk_fma_f32 v[186:187], v[22:23], v[202:203], v[186:187]
	v_pk_fma_f32 v[188:189], v[34:35], v[202:203], v[188:189]
	v_pk_fma_f32 v[190:191], v[20:21], v[202:203], v[190:191]
	v_pk_fma_f32 v[192:193], v[18:19], v[202:203], v[192:193]
	v_pk_fma_f32 v[194:195], v[16:17], v[202:203], v[194:195]
	v_pk_fma_f32 v[196:197], v[32:33], v[202:203], v[196:197]
	v_pk_fma_f32 v[198:199], v[76:77], v[202:203], v[198:199]
	v_pk_fma_f32 v[200:201], v[74:75], v[202:203], v[200:201]
	v_pk_fma_f32 v[202:203], v[72:73], v[202:203], v[78:79]
	v_lshlrev_b32_e32 v204, 16, v90
	v_and_b32_e32 v205, 0xffff0000, v90
	v_pk_fma_f32 v[180:181], v[28:29], v[204:205], v[180:181]
	v_pk_fma_f32 v[182:183], v[36:37], v[204:205], v[182:183]
	v_pk_fma_f32 v[184:185], v[26:27], v[204:205], v[184:185]
	v_pk_fma_f32 v[186:187], v[24:25], v[204:205], v[186:187]
	v_pk_fma_f32 v[188:189], v[22:23], v[204:205], v[188:189]
	v_pk_fma_f32 v[190:191], v[34:35], v[204:205], v[190:191]
	v_pk_fma_f32 v[192:193], v[20:21], v[204:205], v[192:193]
	v_pk_fma_f32 v[194:195], v[18:19], v[204:205], v[194:195]
	v_pk_fma_f32 v[196:197], v[16:17], v[204:205], v[196:197]
	v_pk_fma_f32 v[198:199], v[32:33], v[204:205], v[198:199]
	v_pk_fma_f32 v[200:201], v[76:77], v[204:205], v[200:201]
	v_pk_fma_f32 v[202:203], v[74:75], v[204:205], v[202:203]
	v_pk_fma_f32 v[204:205], v[72:73], v[204:205], v[78:79]
	v_lshlrev_b32_e32 v206, 16, v91
	v_and_b32_e32 v207, 0xffff0000, v91
	v_pk_fma_f32 v[180:181], v[30:31], v[206:207], v[180:181]
	v_pk_fma_f32 v[182:183], v[28:29], v[206:207], v[182:183]
	v_pk_fma_f32 v[184:185], v[36:37], v[206:207], v[184:185]
	v_pk_fma_f32 v[186:187], v[26:27], v[206:207], v[186:187]
	v_pk_fma_f32 v[188:189], v[24:25], v[206:207], v[188:189]
	v_pk_fma_f32 v[190:191], v[22:23], v[206:207], v[190:191]
	v_pk_fma_f32 v[192:193], v[34:35], v[206:207], v[192:193]
	v_pk_fma_f32 v[194:195], v[20:21], v[206:207], v[194:195]
	v_pk_fma_f32 v[196:197], v[18:19], v[206:207], v[196:197]
	v_pk_fma_f32 v[198:199], v[16:17], v[206:207], v[198:199]
	v_pk_fma_f32 v[200:201], v[32:33], v[206:207], v[200:201]
	v_pk_fma_f32 v[202:203], v[76:77], v[206:207], v[202:203]
	v_pk_fma_f32 v[204:205], v[74:75], v[206:207], v[204:205]
	v_pk_fma_f32 v[206:207], v[72:73], v[206:207], v[78:79]
	v_lshlrev_b32_e32 v208, 16, v92
	v_and_b32_e32 v209, 0xffff0000, v92
	v_pk_fma_f32 v[180:181], v[40:41], v[208:209], v[180:181]
	v_pk_fma_f32 v[182:183], v[30:31], v[208:209], v[182:183]
	v_pk_fma_f32 v[184:185], v[28:29], v[208:209], v[184:185]
	v_pk_fma_f32 v[186:187], v[36:37], v[208:209], v[186:187]
	v_pk_fma_f32 v[188:189], v[26:27], v[208:209], v[188:189]
	v_pk_fma_f32 v[190:191], v[24:25], v[208:209], v[190:191]
	v_pk_fma_f32 v[192:193], v[22:23], v[208:209], v[192:193]
	v_pk_fma_f32 v[194:195], v[34:35], v[208:209], v[194:195]
	v_pk_fma_f32 v[196:197], v[20:21], v[208:209], v[196:197]
	v_pk_fma_f32 v[198:199], v[18:19], v[208:209], v[198:199]
	v_pk_fma_f32 v[200:201], v[16:17], v[208:209], v[200:201]
	v_pk_fma_f32 v[202:203], v[32:33], v[208:209], v[202:203]
	v_pk_fma_f32 v[204:205], v[76:77], v[208:209], v[204:205]
	v_pk_fma_f32 v[206:207], v[74:75], v[208:209], v[206:207]
	v_pk_fma_f32 v[208:209], v[72:73], v[208:209], v[78:79]
	v_lshlrev_b32_e32 v210, 16, v93
	v_and_b32_e32 v211, 0xffff0000, v93
	v_pk_fma_f32 v[180:181], v[38:39], v[210:211], v[180:181]
	v_pk_fma_f32 v[182:183], v[40:41], v[210:211], v[182:183]
	v_pk_fma_f32 v[184:185], v[30:31], v[210:211], v[184:185]
	v_pk_fma_f32 v[186:187], v[28:29], v[210:211], v[186:187]
	v_pk_fma_f32 v[188:189], v[36:37], v[210:211], v[188:189]
	v_pk_fma_f32 v[190:191], v[26:27], v[210:211], v[190:191]
	v_pk_fma_f32 v[192:193], v[24:25], v[210:211], v[192:193]
	v_pk_fma_f32 v[194:195], v[22:23], v[210:211], v[194:195]
	v_pk_fma_f32 v[196:197], v[34:35], v[210:211], v[196:197]
	v_pk_fma_f32 v[198:199], v[20:21], v[210:211], v[198:199]
	v_pk_fma_f32 v[200:201], v[18:19], v[210:211], v[200:201]
	v_pk_fma_f32 v[202:203], v[16:17], v[210:211], v[202:203]
	v_pk_fma_f32 v[204:205], v[32:33], v[210:211], v[204:205]
	v_pk_fma_f32 v[206:207], v[76:77], v[210:211], v[206:207]
	v_pk_fma_f32 v[208:209], v[74:75], v[210:211], v[208:209]
	v_pk_fma_f32 v[210:211], v[72:73], v[210:211], v[78:79]
	v_lshlrev_b32_e32 v212, 16, v94
	v_and_b32_e32 v213, 0xffff0000, v94
	v_pk_fma_f32 v[180:181], v[42:43], v[212:213], v[180:181]
	v_pk_fma_f32 v[182:183], v[38:39], v[212:213], v[182:183]
	v_pk_fma_f32 v[184:185], v[40:41], v[212:213], v[184:185]
	v_pk_fma_f32 v[186:187], v[30:31], v[212:213], v[186:187]
	v_pk_fma_f32 v[188:189], v[28:29], v[212:213], v[188:189]
	v_pk_fma_f32 v[190:191], v[36:37], v[212:213], v[190:191]
	v_pk_fma_f32 v[192:193], v[26:27], v[212:213], v[192:193]
	v_pk_fma_f32 v[194:195], v[24:25], v[212:213], v[194:195]
	v_pk_fma_f32 v[196:197], v[22:23], v[212:213], v[196:197]
	v_pk_fma_f32 v[198:199], v[34:35], v[212:213], v[198:199]
	v_pk_fma_f32 v[200:201], v[20:21], v[212:213], v[200:201]
	v_pk_fma_f32 v[202:203], v[18:19], v[212:213], v[202:203]
	v_pk_fma_f32 v[204:205], v[16:17], v[212:213], v[204:205]
	v_pk_fma_f32 v[206:207], v[32:33], v[212:213], v[206:207]
	v_pk_fma_f32 v[208:209], v[76:77], v[212:213], v[208:209]
	v_pk_fma_f32 v[210:211], v[74:75], v[212:213], v[210:211]
	v_lshlrev_b32_e32 v212, 16, v95
	v_and_b32_e32 v213, 0xffff0000, v95
	v_pk_fma_f32 v[180:181], v[44:45], v[212:213], v[180:181]
	v_pk_fma_f32 v[182:183], v[42:43], v[212:213], v[182:183]
	v_pk_fma_f32 v[184:185], v[38:39], v[212:213], v[184:185]
	v_pk_fma_f32 v[186:187], v[40:41], v[212:213], v[186:187]
	v_pk_fma_f32 v[188:189], v[30:31], v[212:213], v[188:189]
	v_pk_fma_f32 v[190:191], v[28:29], v[212:213], v[190:191]
	v_pk_fma_f32 v[192:193], v[36:37], v[212:213], v[192:193]
	v_pk_fma_f32 v[194:195], v[26:27], v[212:213], v[194:195]
	v_pk_fma_f32 v[196:197], v[24:25], v[212:213], v[196:197]
	v_pk_fma_f32 v[198:199], v[22:23], v[212:213], v[198:199]
	v_pk_fma_f32 v[200:201], v[34:35], v[212:213], v[200:201]
	v_pk_fma_f32 v[202:203], v[20:21], v[212:213], v[202:203]
	v_pk_fma_f32 v[204:205], v[18:19], v[212:213], v[204:205]
	v_pk_fma_f32 v[206:207], v[16:17], v[212:213], v[206:207]
	v_pk_fma_f32 v[208:209], v[32:33], v[212:213], v[208:209]
	v_pk_fma_f32 v[210:211], v[76:77], v[212:213], v[210:211]
	v_lshlrev_b32_e32 v212, 16, v96
	v_and_b32_e32 v213, 0xffff0000, v96
	v_pk_fma_f32 v[180:181], v[46:47], v[212:213], v[180:181]
	v_pk_fma_f32 v[182:183], v[44:45], v[212:213], v[182:183]
	v_pk_fma_f32 v[184:185], v[42:43], v[212:213], v[184:185]
	v_pk_fma_f32 v[186:187], v[38:39], v[212:213], v[186:187]
	v_pk_fma_f32 v[188:189], v[40:41], v[212:213], v[188:189]
	v_pk_fma_f32 v[190:191], v[30:31], v[212:213], v[190:191]
	v_pk_fma_f32 v[192:193], v[28:29], v[212:213], v[192:193]
	v_pk_fma_f32 v[194:195], v[36:37], v[212:213], v[194:195]
	v_pk_fma_f32 v[196:197], v[26:27], v[212:213], v[196:197]
	v_pk_fma_f32 v[198:199], v[24:25], v[212:213], v[198:199]
	v_pk_fma_f32 v[200:201], v[22:23], v[212:213], v[200:201]
	v_pk_fma_f32 v[202:203], v[34:35], v[212:213], v[202:203]
	v_pk_fma_f32 v[204:205], v[20:21], v[212:213], v[204:205]
	v_pk_fma_f32 v[206:207], v[18:19], v[212:213], v[206:207]
	v_pk_fma_f32 v[208:209], v[16:17], v[212:213], v[208:209]
	v_pk_fma_f32 v[210:211], v[32:33], v[212:213], v[210:211]
	v_lshlrev_b32_e32 v212, 16, v97
	v_and_b32_e32 v213, 0xffff0000, v97
	v_pk_fma_f32 v[180:181], v[64:65], v[212:213], v[180:181]
	v_pk_fma_f32 v[182:183], v[46:47], v[212:213], v[182:183]
	v_pk_fma_f32 v[184:185], v[44:45], v[212:213], v[184:185]
	v_pk_fma_f32 v[186:187], v[42:43], v[212:213], v[186:187]
	v_pk_fma_f32 v[188:189], v[38:39], v[212:213], v[188:189]
	v_pk_fma_f32 v[190:191], v[40:41], v[212:213], v[190:191]
	v_pk_fma_f32 v[192:193], v[30:31], v[212:213], v[192:193]
	v_pk_fma_f32 v[194:195], v[28:29], v[212:213], v[194:195]
	v_pk_fma_f32 v[196:197], v[36:37], v[212:213], v[196:197]
	v_pk_fma_f32 v[198:199], v[26:27], v[212:213], v[198:199]
	v_pk_fma_f32 v[200:201], v[24:25], v[212:213], v[200:201]
	v_pk_fma_f32 v[202:203], v[22:23], v[212:213], v[202:203]
	v_pk_fma_f32 v[204:205], v[34:35], v[212:213], v[204:205]
	v_pk_fma_f32 v[206:207], v[20:21], v[212:213], v[206:207]
	v_pk_fma_f32 v[208:209], v[18:19], v[212:213], v[208:209]
	v_pk_fma_f32 v[210:211], v[16:17], v[212:213], v[210:211]
	v_lshlrev_b32_e32 v212, 16, v98
	v_and_b32_e32 v213, 0xffff0000, v98
	v_pk_fma_f32 v[180:181], v[48:49], v[212:213], v[180:181]
	v_pk_fma_f32 v[182:183], v[64:65], v[212:213], v[182:183]
	v_pk_fma_f32 v[184:185], v[46:47], v[212:213], v[184:185]
	v_pk_fma_f32 v[186:187], v[44:45], v[212:213], v[186:187]
	v_pk_fma_f32 v[188:189], v[42:43], v[212:213], v[188:189]
	v_pk_fma_f32 v[190:191], v[38:39], v[212:213], v[190:191]
	v_pk_fma_f32 v[192:193], v[40:41], v[212:213], v[192:193]
	v_pk_fma_f32 v[194:195], v[30:31], v[212:213], v[194:195]
	v_pk_fma_f32 v[196:197], v[28:29], v[212:213], v[196:197]
	v_pk_fma_f32 v[198:199], v[36:37], v[212:213], v[198:199]
	v_pk_fma_f32 v[200:201], v[26:27], v[212:213], v[200:201]
	v_pk_fma_f32 v[202:203], v[24:25], v[212:213], v[202:203]
	v_pk_fma_f32 v[204:205], v[22:23], v[212:213], v[204:205]
	v_pk_fma_f32 v[206:207], v[34:35], v[212:213], v[206:207]
	v_pk_fma_f32 v[208:209], v[20:21], v[212:213], v[208:209]
	v_pk_fma_f32 v[210:211], v[18:19], v[212:213], v[210:211]
	v_lshlrev_b32_e32 v212, 16, v99
	v_and_b32_e32 v213, 0xffff0000, v99
	v_pk_fma_f32 v[180:181], v[50:51], v[212:213], v[180:181]
	v_pk_fma_f32 v[182:183], v[48:49], v[212:213], v[182:183]
	v_pk_fma_f32 v[184:185], v[64:65], v[212:213], v[184:185]
	v_pk_fma_f32 v[186:187], v[46:47], v[212:213], v[186:187]
	v_pk_fma_f32 v[188:189], v[44:45], v[212:213], v[188:189]
	v_pk_fma_f32 v[190:191], v[42:43], v[212:213], v[190:191]
	v_pk_fma_f32 v[192:193], v[38:39], v[212:213], v[192:193]
	v_pk_fma_f32 v[194:195], v[40:41], v[212:213], v[194:195]
	v_pk_fma_f32 v[196:197], v[30:31], v[212:213], v[196:197]
	v_pk_fma_f32 v[198:199], v[28:29], v[212:213], v[198:199]
	v_pk_fma_f32 v[200:201], v[36:37], v[212:213], v[200:201]
	v_pk_fma_f32 v[202:203], v[26:27], v[212:213], v[202:203]
	v_pk_fma_f32 v[204:205], v[24:25], v[212:213], v[204:205]
	v_pk_fma_f32 v[206:207], v[22:23], v[212:213], v[206:207]
	v_pk_fma_f32 v[208:209], v[34:35], v[212:213], v[208:209]
	v_pk_fma_f32 v[210:211], v[20:21], v[212:213], v[210:211]
	v_lshlrev_b32_e32 v212, 16, v100
	v_and_b32_e32 v213, 0xffff0000, v100
	v_pk_fma_f32 v[180:181], v[52:53], v[212:213], v[180:181]
	v_pk_fma_f32 v[182:183], v[50:51], v[212:213], v[182:183]
	v_pk_fma_f32 v[184:185], v[48:49], v[212:213], v[184:185]
	v_pk_fma_f32 v[186:187], v[64:65], v[212:213], v[186:187]
	v_pk_fma_f32 v[188:189], v[46:47], v[212:213], v[188:189]
	v_pk_fma_f32 v[190:191], v[44:45], v[212:213], v[190:191]
	v_pk_fma_f32 v[192:193], v[42:43], v[212:213], v[192:193]
	v_pk_fma_f32 v[194:195], v[38:39], v[212:213], v[194:195]
	v_pk_fma_f32 v[196:197], v[40:41], v[212:213], v[196:197]
	v_pk_fma_f32 v[198:199], v[30:31], v[212:213], v[198:199]
	v_pk_fma_f32 v[200:201], v[28:29], v[212:213], v[200:201]
	v_pk_fma_f32 v[202:203], v[36:37], v[212:213], v[202:203]
	v_pk_fma_f32 v[204:205], v[26:27], v[212:213], v[204:205]
	v_pk_fma_f32 v[206:207], v[24:25], v[212:213], v[206:207]
	v_pk_fma_f32 v[208:209], v[22:23], v[212:213], v[208:209]
	v_pk_fma_f32 v[210:211], v[34:35], v[212:213], v[210:211]
	v_lshlrev_b32_e32 v212, 16, v117
	v_and_b32_e32 v213, 0xffff0000, v117
	v_pk_fma_f32 v[180:181], v[66:67], v[212:213], v[180:181]
	v_pk_fma_f32 v[182:183], v[52:53], v[212:213], v[182:183]
	v_pk_fma_f32 v[184:185], v[50:51], v[212:213], v[184:185]
	v_pk_fma_f32 v[186:187], v[48:49], v[212:213], v[186:187]
	v_pk_fma_f32 v[188:189], v[64:65], v[212:213], v[188:189]
	v_pk_fma_f32 v[190:191], v[46:47], v[212:213], v[190:191]
	v_pk_fma_f32 v[192:193], v[44:45], v[212:213], v[192:193]
	v_pk_fma_f32 v[194:195], v[42:43], v[212:213], v[194:195]
	v_pk_fma_f32 v[196:197], v[38:39], v[212:213], v[196:197]
	v_pk_fma_f32 v[198:199], v[40:41], v[212:213], v[198:199]
	v_pk_fma_f32 v[200:201], v[30:31], v[212:213], v[200:201]
	v_pk_fma_f32 v[202:203], v[28:29], v[212:213], v[202:203]
	v_pk_fma_f32 v[204:205], v[36:37], v[212:213], v[204:205]
	v_pk_fma_f32 v[206:207], v[26:27], v[212:213], v[206:207]
	v_pk_fma_f32 v[208:209], v[24:25], v[212:213], v[208:209]
	v_pk_fma_f32 v[210:211], v[22:23], v[212:213], v[210:211]
	v_lshlrev_b32_e32 v212, 16, v110
	v_and_b32_e32 v213, 0xffff0000, v110
	v_pk_fma_f32 v[180:181], v[54:55], v[212:213], v[180:181]
	v_pk_fma_f32 v[182:183], v[66:67], v[212:213], v[182:183]
	v_pk_fma_f32 v[184:185], v[52:53], v[212:213], v[184:185]
	v_pk_fma_f32 v[186:187], v[50:51], v[212:213], v[186:187]
	v_pk_fma_f32 v[188:189], v[48:49], v[212:213], v[188:189]
	v_pk_fma_f32 v[190:191], v[64:65], v[212:213], v[190:191]
	v_pk_fma_f32 v[192:193], v[46:47], v[212:213], v[192:193]
	v_pk_fma_f32 v[194:195], v[44:45], v[212:213], v[194:195]
	v_pk_fma_f32 v[196:197], v[42:43], v[212:213], v[196:197]
	v_pk_fma_f32 v[198:199], v[38:39], v[212:213], v[198:199]
	v_pk_fma_f32 v[200:201], v[40:41], v[212:213], v[200:201]
	v_pk_fma_f32 v[202:203], v[30:31], v[212:213], v[202:203]
	v_pk_fma_f32 v[204:205], v[28:29], v[212:213], v[204:205]
	v_pk_fma_f32 v[206:207], v[36:37], v[212:213], v[206:207]
	v_pk_fma_f32 v[208:209], v[26:27], v[212:213], v[208:209]
	v_pk_fma_f32 v[210:211], v[24:25], v[212:213], v[210:211]
	v_lshlrev_b32_e32 v212, 16, v111
	v_and_b32_e32 v213, 0xffff0000, v111
	v_pk_fma_f32 v[180:181], v[56:57], v[212:213], v[180:181]
	v_pk_fma_f32 v[182:183], v[54:55], v[212:213], v[182:183]
	v_pk_fma_f32 v[184:185], v[66:67], v[212:213], v[184:185]
	v_pk_fma_f32 v[186:187], v[52:53], v[212:213], v[186:187]
	v_pk_fma_f32 v[188:189], v[50:51], v[212:213], v[188:189]
	v_pk_fma_f32 v[190:191], v[48:49], v[212:213], v[190:191]
	v_pk_fma_f32 v[192:193], v[64:65], v[212:213], v[192:193]
	v_pk_fma_f32 v[194:195], v[46:47], v[212:213], v[194:195]
	v_pk_fma_f32 v[196:197], v[44:45], v[212:213], v[196:197]
	v_pk_fma_f32 v[198:199], v[42:43], v[212:213], v[198:199]
	v_pk_fma_f32 v[200:201], v[38:39], v[212:213], v[200:201]
	v_pk_fma_f32 v[202:203], v[40:41], v[212:213], v[202:203]
	v_pk_fma_f32 v[204:205], v[30:31], v[212:213], v[204:205]
	v_pk_fma_f32 v[206:207], v[28:29], v[212:213], v[206:207]
	v_pk_fma_f32 v[208:209], v[36:37], v[212:213], v[208:209]
	v_pk_fma_f32 v[210:211], v[26:27], v[212:213], v[210:211]
	v_lshlrev_b32_e32 v212, 16, v112
	v_and_b32_e32 v213, 0xffff0000, v112
	v_pk_fma_f32 v[180:181], v[58:59], v[212:213], v[180:181]
	v_pk_fma_f32 v[182:183], v[56:57], v[212:213], v[182:183]
	v_pk_fma_f32 v[184:185], v[54:55], v[212:213], v[184:185]
	v_pk_fma_f32 v[186:187], v[66:67], v[212:213], v[186:187]
	v_pk_fma_f32 v[188:189], v[52:53], v[212:213], v[188:189]
	v_pk_fma_f32 v[190:191], v[50:51], v[212:213], v[190:191]
	v_pk_fma_f32 v[192:193], v[48:49], v[212:213], v[192:193]
	v_pk_fma_f32 v[194:195], v[64:65], v[212:213], v[194:195]
	v_pk_fma_f32 v[196:197], v[46:47], v[212:213], v[196:197]
	v_pk_fma_f32 v[198:199], v[44:45], v[212:213], v[198:199]
	v_pk_fma_f32 v[200:201], v[42:43], v[212:213], v[200:201]
	v_pk_fma_f32 v[202:203], v[38:39], v[212:213], v[202:203]
	v_pk_fma_f32 v[204:205], v[40:41], v[212:213], v[204:205]
	v_pk_fma_f32 v[206:207], v[30:31], v[212:213], v[206:207]
	v_pk_fma_f32 v[208:209], v[28:29], v[212:213], v[208:209]
	v_pk_fma_f32 v[210:211], v[36:37], v[212:213], v[210:211]
	v_lshlrev_b32_e32 v212, 16, v113
	v_and_b32_e32 v213, 0xffff0000, v113
	v_pk_fma_f32 v[180:181], v[68:69], v[212:213], v[180:181]
	v_pk_fma_f32 v[182:183], v[58:59], v[212:213], v[182:183]
	v_pk_fma_f32 v[184:185], v[56:57], v[212:213], v[184:185]
	v_pk_fma_f32 v[186:187], v[54:55], v[212:213], v[186:187]
	v_pk_fma_f32 v[188:189], v[66:67], v[212:213], v[188:189]
	v_pk_fma_f32 v[190:191], v[52:53], v[212:213], v[190:191]
	v_pk_fma_f32 v[192:193], v[50:51], v[212:213], v[192:193]
	v_pk_fma_f32 v[194:195], v[48:49], v[212:213], v[194:195]
	v_pk_fma_f32 v[196:197], v[64:65], v[212:213], v[196:197]
	v_pk_fma_f32 v[198:199], v[46:47], v[212:213], v[198:199]
	v_pk_fma_f32 v[200:201], v[44:45], v[212:213], v[200:201]
	v_pk_fma_f32 v[202:203], v[42:43], v[212:213], v[202:203]
	v_pk_fma_f32 v[204:205], v[38:39], v[212:213], v[204:205]
	v_pk_fma_f32 v[206:207], v[40:41], v[212:213], v[206:207]
	v_pk_fma_f32 v[208:209], v[30:31], v[212:213], v[208:209]
	v_pk_fma_f32 v[210:211], v[28:29], v[212:213], v[210:211]
	v_lshlrev_b32_e32 v212, 16, v116
	v_and_b32_e32 v213, 0xffff0000, v116
	v_pk_fma_f32 v[180:181], v[60:61], v[212:213], v[180:181]
	v_pk_fma_f32 v[182:183], v[68:69], v[212:213], v[182:183]
	v_pk_fma_f32 v[184:185], v[58:59], v[212:213], v[184:185]
	v_pk_fma_f32 v[186:187], v[56:57], v[212:213], v[186:187]
	v_pk_fma_f32 v[188:189], v[54:55], v[212:213], v[188:189]
	v_pk_fma_f32 v[190:191], v[66:67], v[212:213], v[190:191]
	v_pk_fma_f32 v[192:193], v[52:53], v[212:213], v[192:193]
	v_pk_fma_f32 v[194:195], v[50:51], v[212:213], v[194:195]
	v_pk_fma_f32 v[196:197], v[48:49], v[212:213], v[196:197]
	v_pk_fma_f32 v[198:199], v[64:65], v[212:213], v[198:199]
	v_pk_fma_f32 v[200:201], v[46:47], v[212:213], v[200:201]
	v_pk_fma_f32 v[202:203], v[44:45], v[212:213], v[202:203]
	v_pk_fma_f32 v[204:205], v[42:43], v[212:213], v[204:205]
	v_pk_fma_f32 v[206:207], v[38:39], v[212:213], v[206:207]
	v_pk_fma_f32 v[208:209], v[40:41], v[212:213], v[208:209]
	v_pk_fma_f32 v[210:211], v[30:31], v[212:213], v[210:211]
	v_lshlrev_b32_e32 v212, 16, v121
	v_and_b32_e32 v213, 0xffff0000, v121
	v_pk_fma_f32 v[180:181], v[62:63], v[212:213], v[180:181]
	v_pk_fma_f32 v[182:183], v[60:61], v[212:213], v[182:183]
	v_pk_fma_f32 v[184:185], v[68:69], v[212:213], v[184:185]
	v_pk_fma_f32 v[186:187], v[58:59], v[212:213], v[186:187]
	v_pk_fma_f32 v[188:189], v[56:57], v[212:213], v[188:189]
	v_pk_fma_f32 v[190:191], v[54:55], v[212:213], v[190:191]
	v_pk_fma_f32 v[192:193], v[66:67], v[212:213], v[192:193]
	v_pk_fma_f32 v[194:195], v[52:53], v[212:213], v[194:195]
	v_pk_fma_f32 v[196:197], v[50:51], v[212:213], v[196:197]
	v_pk_fma_f32 v[198:199], v[48:49], v[212:213], v[198:199]
	v_pk_fma_f32 v[200:201], v[64:65], v[212:213], v[200:201]
	v_pk_fma_f32 v[202:203], v[46:47], v[212:213], v[202:203]
	v_pk_fma_f32 v[204:205], v[44:45], v[212:213], v[204:205]
	v_pk_fma_f32 v[206:207], v[42:43], v[212:213], v[206:207]
	v_pk_fma_f32 v[208:209], v[38:39], v[212:213], v[208:209]
	v_pk_fma_f32 v[210:211], v[40:41], v[212:213], v[210:211]
	v_lshlrev_b32_e32 v212, 16, v122
	v_and_b32_e32 v213, 0xffff0000, v122
	v_pk_fma_f32 v[180:181], v[70:71], v[212:213], v[180:181]
	v_pk_fma_f32 v[182:183], v[62:63], v[212:213], v[182:183]
	v_pk_fma_f32 v[184:185], v[60:61], v[212:213], v[184:185]
	v_pk_fma_f32 v[186:187], v[68:69], v[212:213], v[186:187]
	v_pk_fma_f32 v[188:189], v[58:59], v[212:213], v[188:189]
	v_pk_fma_f32 v[190:191], v[56:57], v[212:213], v[190:191]
	v_pk_fma_f32 v[192:193], v[54:55], v[212:213], v[192:193]
	v_pk_fma_f32 v[194:195], v[66:67], v[212:213], v[194:195]
	v_pk_fma_f32 v[196:197], v[52:53], v[212:213], v[196:197]
	v_pk_fma_f32 v[198:199], v[50:51], v[212:213], v[198:199]
	v_pk_fma_f32 v[200:201], v[48:49], v[212:213], v[200:201]
	v_pk_fma_f32 v[202:203], v[64:65], v[212:213], v[202:203]
	v_pk_fma_f32 v[204:205], v[46:47], v[212:213], v[204:205]
	v_pk_fma_f32 v[206:207], v[44:45], v[212:213], v[206:207]
	v_pk_fma_f32 v[208:209], v[42:43], v[212:213], v[208:209]
	v_pk_fma_f32 v[210:211], v[38:39], v[212:213], v[210:211]
	v_lshlrev_b32_e32 v212, 16, v124
	v_and_b32_e32 v213, 0xffff0000, v124
	v_pk_fma_f32 v[182:183], v[70:71], v[212:213], v[182:183]
	v_pk_fma_f32 v[184:185], v[62:63], v[212:213], v[184:185]
	v_pk_fma_f32 v[186:187], v[60:61], v[212:213], v[186:187]
	v_pk_fma_f32 v[188:189], v[68:69], v[212:213], v[188:189]
	v_pk_fma_f32 v[190:191], v[58:59], v[212:213], v[190:191]
	v_pk_fma_f32 v[192:193], v[56:57], v[212:213], v[192:193]
	v_pk_fma_f32 v[194:195], v[54:55], v[212:213], v[194:195]
	v_pk_fma_f32 v[196:197], v[66:67], v[212:213], v[196:197]
	v_pk_fma_f32 v[198:199], v[52:53], v[212:213], v[198:199]
	v_pk_fma_f32 v[200:201], v[50:51], v[212:213], v[200:201]
	v_pk_fma_f32 v[202:203], v[48:49], v[212:213], v[202:203]
	v_pk_fma_f32 v[204:205], v[64:65], v[212:213], v[204:205]
	v_pk_fma_f32 v[206:207], v[46:47], v[212:213], v[206:207]
	v_pk_fma_f32 v[208:209], v[44:45], v[212:213], v[208:209]
	v_pk_fma_f32 v[210:211], v[42:43], v[212:213], v[210:211]
	v_lshlrev_b32_e32 v212, 16, v118
	v_and_b32_e32 v213, 0xffff0000, v118
	v_pk_fma_f32 v[184:185], v[70:71], v[212:213], v[184:185]
	v_pk_fma_f32 v[186:187], v[62:63], v[212:213], v[186:187]
	v_pk_fma_f32 v[188:189], v[60:61], v[212:213], v[188:189]
	v_pk_fma_f32 v[190:191], v[68:69], v[212:213], v[190:191]
	v_pk_fma_f32 v[192:193], v[58:59], v[212:213], v[192:193]
	v_pk_fma_f32 v[194:195], v[56:57], v[212:213], v[194:195]
	v_pk_fma_f32 v[196:197], v[54:55], v[212:213], v[196:197]
	v_pk_fma_f32 v[198:199], v[66:67], v[212:213], v[198:199]
	v_pk_fma_f32 v[200:201], v[52:53], v[212:213], v[200:201]
	v_pk_fma_f32 v[202:203], v[50:51], v[212:213], v[202:203]
	v_pk_fma_f32 v[204:205], v[48:49], v[212:213], v[204:205]
	v_pk_fma_f32 v[206:207], v[64:65], v[212:213], v[206:207]
	v_pk_fma_f32 v[208:209], v[46:47], v[212:213], v[208:209]
	v_pk_fma_f32 v[210:211], v[44:45], v[212:213], v[210:211]
	v_lshlrev_b32_e32 v212, 16, v119
	v_and_b32_e32 v213, 0xffff0000, v119
	v_pk_fma_f32 v[186:187], v[70:71], v[212:213], v[186:187]
	v_pk_fma_f32 v[188:189], v[62:63], v[212:213], v[188:189]
	v_pk_fma_f32 v[190:191], v[60:61], v[212:213], v[190:191]
	v_pk_fma_f32 v[192:193], v[68:69], v[212:213], v[192:193]
	v_pk_fma_f32 v[194:195], v[58:59], v[212:213], v[194:195]
	v_pk_fma_f32 v[196:197], v[56:57], v[212:213], v[196:197]
	v_pk_fma_f32 v[198:199], v[54:55], v[212:213], v[198:199]
	v_pk_fma_f32 v[200:201], v[66:67], v[212:213], v[200:201]
	v_pk_fma_f32 v[202:203], v[52:53], v[212:213], v[202:203]
	v_pk_fma_f32 v[204:205], v[50:51], v[212:213], v[204:205]
	v_pk_fma_f32 v[206:207], v[48:49], v[212:213], v[206:207]
	v_pk_fma_f32 v[208:209], v[64:65], v[212:213], v[208:209]
	v_pk_fma_f32 v[210:211], v[46:47], v[212:213], v[210:211]
	v_lshlrev_b32_e32 v212, 16, v120
	v_and_b32_e32 v213, 0xffff0000, v120
	v_pk_fma_f32 v[188:189], v[70:71], v[212:213], v[188:189]
	v_pk_fma_f32 v[190:191], v[62:63], v[212:213], v[190:191]
	v_pk_fma_f32 v[192:193], v[60:61], v[212:213], v[192:193]
	v_pk_fma_f32 v[194:195], v[68:69], v[212:213], v[194:195]
	v_pk_fma_f32 v[196:197], v[58:59], v[212:213], v[196:197]
	v_pk_fma_f32 v[198:199], v[56:57], v[212:213], v[198:199]
	v_pk_fma_f32 v[200:201], v[54:55], v[212:213], v[200:201]
	v_pk_fma_f32 v[202:203], v[66:67], v[212:213], v[202:203]
	v_pk_fma_f32 v[204:205], v[52:53], v[212:213], v[204:205]
	v_pk_fma_f32 v[206:207], v[50:51], v[212:213], v[206:207]
	v_pk_fma_f32 v[208:209], v[48:49], v[212:213], v[208:209]
	v_pk_fma_f32 v[210:211], v[64:65], v[212:213], v[210:211]
	v_lshlrev_b32_e32 v212, 16, v123
	v_and_b32_e32 v213, 0xffff0000, v123
	v_pk_fma_f32 v[190:191], v[70:71], v[212:213], v[190:191]
	v_pk_fma_f32 v[192:193], v[62:63], v[212:213], v[192:193]
	v_pk_fma_f32 v[194:195], v[60:61], v[212:213], v[194:195]
	v_pk_fma_f32 v[196:197], v[68:69], v[212:213], v[196:197]
	v_pk_fma_f32 v[198:199], v[58:59], v[212:213], v[198:199]
	v_pk_fma_f32 v[200:201], v[56:57], v[212:213], v[200:201]
	v_pk_fma_f32 v[202:203], v[54:55], v[212:213], v[202:203]
	v_pk_fma_f32 v[204:205], v[66:67], v[212:213], v[204:205]
	v_pk_fma_f32 v[206:207], v[52:53], v[212:213], v[206:207]
	v_pk_fma_f32 v[208:209], v[50:51], v[212:213], v[208:209]
	v_pk_fma_f32 v[210:211], v[48:49], v[212:213], v[210:211]
	v_lshlrev_b32_e32 v212, 16, v125
	v_and_b32_e32 v213, 0xffff0000, v125
	v_pk_fma_f32 v[192:193], v[70:71], v[212:213], v[192:193]
	v_pk_fma_f32 v[194:195], v[62:63], v[212:213], v[194:195]
	v_pk_fma_f32 v[196:197], v[60:61], v[212:213], v[196:197]
	v_pk_fma_f32 v[198:199], v[68:69], v[212:213], v[198:199]
	v_pk_fma_f32 v[200:201], v[58:59], v[212:213], v[200:201]
	v_pk_fma_f32 v[202:203], v[56:57], v[212:213], v[202:203]
	v_pk_fma_f32 v[204:205], v[54:55], v[212:213], v[204:205]
	v_pk_fma_f32 v[206:207], v[66:67], v[212:213], v[206:207]
	v_pk_fma_f32 v[208:209], v[52:53], v[212:213], v[208:209]
	v_pk_fma_f32 v[210:211], v[50:51], v[212:213], v[210:211]
	v_lshlrev_b32_e32 v212, 16, v126
	v_and_b32_e32 v213, 0xffff0000, v126
	v_pk_fma_f32 v[194:195], v[70:71], v[212:213], v[194:195]
	v_pk_fma_f32 v[196:197], v[62:63], v[212:213], v[196:197]
	v_pk_fma_f32 v[198:199], v[60:61], v[212:213], v[198:199]
	v_pk_fma_f32 v[200:201], v[68:69], v[212:213], v[200:201]
	v_pk_fma_f32 v[202:203], v[58:59], v[212:213], v[202:203]
	v_pk_fma_f32 v[204:205], v[56:57], v[212:213], v[204:205]
	v_pk_fma_f32 v[206:207], v[54:55], v[212:213], v[206:207]
	v_pk_fma_f32 v[208:209], v[66:67], v[212:213], v[208:209]
	v_pk_fma_f32 v[210:211], v[52:53], v[212:213], v[210:211]
	v_lshlrev_b32_e32 v212, 16, v127
	v_and_b32_e32 v213, 0xffff0000, v127
	v_pk_fma_f32 v[196:197], v[70:71], v[212:213], v[196:197]
	v_pk_fma_f32 v[198:199], v[62:63], v[212:213], v[198:199]
	v_pk_fma_f32 v[200:201], v[60:61], v[212:213], v[200:201]
	v_pk_fma_f32 v[202:203], v[68:69], v[212:213], v[202:203]
	v_pk_fma_f32 v[204:205], v[58:59], v[212:213], v[204:205]
	v_pk_fma_f32 v[206:207], v[56:57], v[212:213], v[206:207]
	v_pk_fma_f32 v[208:209], v[54:55], v[212:213], v[208:209]
	v_pk_fma_f32 v[210:211], v[66:67], v[212:213], v[210:211]
	v_lshlrev_b32_e32 v212, 16, v129
	v_and_b32_e32 v213, 0xffff0000, v129
	v_pk_fma_f32 v[198:199], v[70:71], v[212:213], v[198:199]
	v_pk_fma_f32 v[200:201], v[62:63], v[212:213], v[200:201]
	v_pk_fma_f32 v[202:203], v[60:61], v[212:213], v[202:203]
	v_pk_fma_f32 v[204:205], v[68:69], v[212:213], v[204:205]
	v_pk_fma_f32 v[206:207], v[58:59], v[212:213], v[206:207]
	v_pk_fma_f32 v[208:209], v[56:57], v[212:213], v[208:209]
	v_pk_fma_f32 v[210:211], v[54:55], v[212:213], v[210:211]
	v_lshlrev_b32_e32 v212, 16, v128
	v_and_b32_e32 v213, 0xffff0000, v128
	v_pk_fma_f32 v[200:201], v[70:71], v[212:213], v[200:201]
	v_pk_fma_f32 v[202:203], v[62:63], v[212:213], v[202:203]
	v_pk_fma_f32 v[204:205], v[60:61], v[212:213], v[204:205]
	v_pk_fma_f32 v[206:207], v[68:69], v[212:213], v[206:207]
	v_pk_fma_f32 v[208:209], v[58:59], v[212:213], v[208:209]
	v_pk_fma_f32 v[210:211], v[56:57], v[212:213], v[210:211]
	v_lshlrev_b32_e32 v212, 16, v130
	v_and_b32_e32 v213, 0xffff0000, v130
	v_pk_fma_f32 v[202:203], v[70:71], v[212:213], v[202:203]
	v_pk_fma_f32 v[204:205], v[62:63], v[212:213], v[204:205]
	v_pk_fma_f32 v[206:207], v[60:61], v[212:213], v[206:207]
	v_pk_fma_f32 v[208:209], v[68:69], v[212:213], v[208:209]
	v_pk_fma_f32 v[210:211], v[58:59], v[212:213], v[210:211]
	v_lshlrev_b32_e32 v212, 16, v131
	v_and_b32_e32 v213, 0xffff0000, v131
	v_pk_fma_f32 v[204:205], v[70:71], v[212:213], v[204:205]
	v_pk_fma_f32 v[206:207], v[62:63], v[212:213], v[206:207]
	v_pk_fma_f32 v[208:209], v[60:61], v[212:213], v[208:209]
	v_pk_fma_f32 v[210:211], v[68:69], v[212:213], v[210:211]
	v_lshlrev_b32_e32 v212, 16, v132
	v_and_b32_e32 v213, 0xffff0000, v132
	s_cmpk_gt_i32 s2, 0x1ff
	v_pk_fma_f32 v[206:207], v[70:71], v[212:213], v[206:207]
	v_pk_fma_f32 v[208:209], v[62:63], v[212:213], v[208:209]
	v_pk_fma_f32 v[210:211], v[60:61], v[212:213], v[210:211]
	v_lshlrev_b32_e32 v212, 16, v133
	v_and_b32_e32 v213, 0xffff0000, v133
	s_cselect_b64 s[0:1], -1, 0
	v_pk_fma_f32 v[208:209], v[70:71], v[212:213], v[208:209]
	v_pk_fma_f32 v[210:211], v[62:63], v[212:213], v[210:211]
	s_waitcnt vmcnt(46)
	v_lshlrev_b32_e32 v212, 16, v134
	v_and_b32_e32 v213, 0xffff0000, v134
	s_and_b64 vcc, exec, s[0:1]
	v_pk_fma_f32 v[210:211], v[70:71], v[212:213], v[210:211]
	ds_write2st64_b64 v108, v[180:181], v[182:183] offset1:4
	ds_write2st64_b64 v108, v[184:185], v[186:187] offset0:8 offset1:12
	ds_write2st64_b64 v108, v[188:189], v[190:191] offset0:16 offset1:20
	ds_write2st64_b64 v108, v[192:193], v[194:195] offset0:24 offset1:28
	ds_write2st64_b64 v108, v[196:197], v[198:199] offset0:32 offset1:36
	ds_write2st64_b64 v108, v[200:201], v[202:203] offset0:40 offset1:44
	ds_write2st64_b64 v108, v[204:205], v[206:207] offset0:48 offset1:52
	ds_write2st64_b64 v108, v[208:209], v[210:211] offset0:56 offset1:60
	s_cbranch_vccnz .LBB0_491
	s_lshl_b32 s9, s2, 6
	s_add_i32 s9, s9, s3
	s_ashr_i32 s10, s9, 13
	s_mulk_i32 s10, 0x2040
	s_and_b32 s9, s9, 0x1fe0
	s_add_i32 s9, s9, s10
	s_add_i32 s10, s9, 34
	s_ashr_i32 s11, s10, 31
	s_lshl_b64 s[10:11], s[10:11], 10
	v_lshl_add_u64 v[130:131], v[82:83], 0, s[10:11]
	v_add_co_u32_e32 v88, vcc, 0x1000, v130
	s_nop 1
	v_addc_co_u32_e32 v89, vcc, 0, v131, vcc
	v_add_co_u32_e32 v90, vcc, 0x2000, v130
	global_load_dword v103, v[130:131], off
	global_load_dword v104, v[130:131], off offset:1024
	global_load_dword v105, v[130:131], off offset:2048
	global_load_dword v106, v[130:131], off offset:3072
	global_load_dword v107, v[88:89], off
	global_load_dword v85, v[88:89], off offset:1024
	global_load_dword v86, v[88:89], off offset:2048
	global_load_dword v87, v[88:89], off offset:3072
	v_addc_co_u32_e32 v91, vcc, 0, v131, vcc
	v_add_co_u32_e32 v94, vcc, 0x3000, v130
	s_nop 1
	v_addc_co_u32_e32 v95, vcc, 0, v131, vcc
	v_add_co_u32_e32 v98, vcc, 0x4000, v130
	global_load_dword v114, v[90:91], off
	global_load_dword v115, v[90:91], off offset:1024
	global_load_dword v88, v[90:91], off offset:2048
	global_load_dword v89, v[90:91], off offset:3072
	s_nop 0
	global_load_dword v90, v[94:95], off
	global_load_dword v91, v[94:95], off offset:1024
	global_load_dword v92, v[94:95], off offset:2048
	global_load_dword v93, v[94:95], off offset:3072
	v_addc_co_u32_e32 v99, vcc, 0, v131, vcc
	v_add_co_u32_e32 v110, vcc, 0x5000, v130
	s_nop 1
	v_addc_co_u32_e32 v111, vcc, 0, v131, vcc
	v_add_co_u32_e32 v118, vcc, 0x6000, v130
	global_load_dword v94, v[98:99], off
	global_load_dword v95, v[98:99], off offset:1024
	global_load_dword v96, v[98:99], off offset:2048
	global_load_dword v97, v[98:99], off offset:3072
	s_nop 0
	global_load_dword v98, v[110:111], off
	global_load_dword v99, v[110:111], off offset:1024
	global_load_dword v100, v[110:111], off offset:2048
	global_load_dword v117, v[110:111], off offset:3072
	v_addc_co_u32_e32 v119, vcc, 0, v131, vcc
	v_add_co_u32_e32 v124, vcc, 0x7000, v130
	s_nop 1
	v_addc_co_u32_e32 v125, vcc, 0, v131, vcc
	v_add_co_u32_e32 v126, vcc, 0x8000, v130
	global_load_dword v110, v[118:119], off
	global_load_dword v111, v[118:119], off offset:1024
	global_load_dword v112, v[118:119], off offset:2048
	global_load_dword v113, v[118:119], off offset:3072
	global_load_dword v116, v[124:125], off
	global_load_dword v121, v[124:125], off offset:1024
	global_load_dword v122, v[124:125], off offset:2048
	s_nop 0
	global_load_dword v124, v[124:125], off offset:3072
	v_addc_co_u32_e32 v127, vcc, 0, v131, vcc
	v_add_co_u32_e32 v128, vcc, 0x9000, v130
	s_nop 1
	v_addc_co_u32_e32 v129, vcc, 0, v131, vcc
	v_add_co_u32_e32 v132, vcc, 0xa000, v130
	global_load_dword v118, v[126:127], off
	global_load_dword v119, v[126:127], off offset:1024
	global_load_dword v120, v[126:127], off offset:2048
	global_load_dword v123, v[126:127], off offset:3072
	global_load_dword v125, v[128:129], off
	s_nop 0
	global_load_dword v126, v[128:129], off offset:1024
	global_load_dword v127, v[128:129], off offset:2048
	s_nop 0
	global_load_dword v129, v[128:129], off offset:3072
	v_addc_co_u32_e32 v133, vcc, 0, v131, vcc
	v_add_co_u32_e32 v180, vcc, 0xb000, v130
	s_nop 1
	v_addc_co_u32_e32 v181, vcc, 0, v131, vcc
	global_load_dword v128, v[132:133], off
	global_load_dword v130, v[132:133], off offset:1024
	global_load_dword v131, v[132:133], off offset:2048
	s_nop 0
	global_load_dword v132, v[132:133], off offset:3072
	s_nop 0
	global_load_dword v133, v[180:181], off
	global_load_dword v134, v[180:181], off offset:1024
	s_waitcnt vmcnt(63)
	v_lshlrev_b32_e32 v180, 16, v179
	v_and_b32_e32 v181, 0xffff0000, v179
	v_pk_fma_f32 v[180:181], v[72:73], v[180:181], v[78:79]
	s_waitcnt vmcnt(63)
	v_lshlrev_b32_e32 v182, 16, v178
	v_and_b32_e32 v183, 0xffff0000, v178
	v_pk_fma_f32 v[178:179], v[74:75], v[182:183], v[180:181]
	v_pk_fma_f32 v[180:181], v[72:73], v[182:183], v[78:79]
	s_waitcnt vmcnt(63)
	v_lshlrev_b32_e32 v182, 16, v177
	v_and_b32_e32 v183, 0xffff0000, v177
	v_pk_fma_f32 v[178:179], v[76:77], v[182:183], v[178:179]
	v_pk_fma_f32 v[180:181], v[74:75], v[182:183], v[180:181]
	v_pk_fma_f32 v[182:183], v[72:73], v[182:183], v[78:79]
	s_waitcnt vmcnt(63)
	v_lshlrev_b32_e32 v184, 16, v176
	v_and_b32_e32 v185, 0xffff0000, v176
	v_pk_fma_f32 v[176:177], v[32:33], v[184:185], v[178:179]
	v_pk_fma_f32 v[178:179], v[76:77], v[184:185], v[180:181]
	v_pk_fma_f32 v[180:181], v[74:75], v[184:185], v[182:183]
	v_pk_fma_f32 v[182:183], v[72:73], v[184:185], v[78:79]
	s_waitcnt vmcnt(63)
	v_lshlrev_b32_e32 v184, 16, v175
	v_and_b32_e32 v185, 0xffff0000, v175
	v_pk_fma_f32 v[176:177], v[16:17], v[184:185], v[176:177]
	v_pk_fma_f32 v[178:179], v[32:33], v[184:185], v[178:179]
	v_pk_fma_f32 v[180:181], v[76:77], v[184:185], v[180:181]
	v_pk_fma_f32 v[182:183], v[74:75], v[184:185], v[182:183]
	v_pk_fma_f32 v[184:185], v[72:73], v[184:185], v[78:79]
	s_waitcnt vmcnt(63)
	v_lshlrev_b32_e32 v186, 16, v174
	v_and_b32_e32 v187, 0xffff0000, v174
	v_pk_fma_f32 v[174:175], v[18:19], v[186:187], v[176:177]
	v_pk_fma_f32 v[176:177], v[16:17], v[186:187], v[178:179]
	v_pk_fma_f32 v[178:179], v[32:33], v[186:187], v[180:181]
	v_pk_fma_f32 v[180:181], v[76:77], v[186:187], v[182:183]
	v_pk_fma_f32 v[182:183], v[74:75], v[186:187], v[184:185]
	v_pk_fma_f32 v[184:185], v[72:73], v[186:187], v[78:79]
	s_waitcnt vmcnt(63)
	v_lshlrev_b32_e32 v186, 16, v173
	v_and_b32_e32 v187, 0xffff0000, v173
	v_pk_fma_f32 v[174:175], v[20:21], v[186:187], v[174:175]
	v_pk_fma_f32 v[176:177], v[18:19], v[186:187], v[176:177]
	v_pk_fma_f32 v[178:179], v[16:17], v[186:187], v[178:179]
	v_pk_fma_f32 v[180:181], v[32:33], v[186:187], v[180:181]
	v_pk_fma_f32 v[182:183], v[76:77], v[186:187], v[182:183]
	v_pk_fma_f32 v[184:185], v[74:75], v[186:187], v[184:185]
	v_pk_fma_f32 v[186:187], v[72:73], v[186:187], v[78:79]
	s_waitcnt vmcnt(63)
	v_lshlrev_b32_e32 v188, 16, v171
	v_and_b32_e32 v189, 0xffff0000, v171
	v_pk_fma_f32 v[174:175], v[34:35], v[188:189], v[174:175]
	v_pk_fma_f32 v[176:177], v[20:21], v[188:189], v[176:177]
	v_pk_fma_f32 v[178:179], v[18:19], v[188:189], v[178:179]
	v_pk_fma_f32 v[180:181], v[16:17], v[188:189], v[180:181]
	v_pk_fma_f32 v[182:183], v[32:33], v[188:189], v[182:183]
	v_pk_fma_f32 v[184:185], v[76:77], v[188:189], v[184:185]
	v_pk_fma_f32 v[186:187], v[74:75], v[188:189], v[186:187]
	v_pk_fma_f32 v[188:189], v[72:73], v[188:189], v[78:79]
	s_waitcnt vmcnt(63)
	v_lshlrev_b32_e32 v190, 16, v172
	v_and_b32_e32 v191, 0xffff0000, v172
	v_pk_fma_f32 v[172:173], v[22:23], v[190:191], v[174:175]
	v_pk_fma_f32 v[174:175], v[34:35], v[190:191], v[176:177]
	v_pk_fma_f32 v[176:177], v[20:21], v[190:191], v[178:179]
	v_pk_fma_f32 v[178:179], v[18:19], v[190:191], v[180:181]
	v_pk_fma_f32 v[180:181], v[16:17], v[190:191], v[182:183]
	v_pk_fma_f32 v[182:183], v[32:33], v[190:191], v[184:185]
	v_pk_fma_f32 v[184:185], v[76:77], v[190:191], v[186:187]
	v_pk_fma_f32 v[186:187], v[74:75], v[190:191], v[188:189]
	v_pk_fma_f32 v[188:189], v[72:73], v[190:191], v[78:79]
	s_waitcnt vmcnt(63)
	v_lshlrev_b32_e32 v190, 16, v170
	v_and_b32_e32 v191, 0xffff0000, v170
	v_pk_fma_f32 v[170:171], v[24:25], v[190:191], v[172:173]
	v_pk_fma_f32 v[172:173], v[22:23], v[190:191], v[174:175]
	v_pk_fma_f32 v[174:175], v[34:35], v[190:191], v[176:177]
	v_pk_fma_f32 v[176:177], v[20:21], v[190:191], v[178:179]
	v_pk_fma_f32 v[178:179], v[18:19], v[190:191], v[180:181]
	v_pk_fma_f32 v[180:181], v[16:17], v[190:191], v[182:183]
	v_pk_fma_f32 v[182:183], v[32:33], v[190:191], v[184:185]
	v_pk_fma_f32 v[184:185], v[76:77], v[190:191], v[186:187]
	v_pk_fma_f32 v[186:187], v[74:75], v[190:191], v[188:189]
	v_pk_fma_f32 v[188:189], v[72:73], v[190:191], v[78:79]
	s_waitcnt vmcnt(63)
	v_lshlrev_b32_e32 v190, 16, v169
	v_and_b32_e32 v191, 0xffff0000, v169
	v_pk_fma_f32 v[170:171], v[26:27], v[190:191], v[170:171]
	v_pk_fma_f32 v[172:173], v[24:25], v[190:191], v[172:173]
	v_pk_fma_f32 v[174:175], v[22:23], v[190:191], v[174:175]
	v_pk_fma_f32 v[176:177], v[34:35], v[190:191], v[176:177]
	v_pk_fma_f32 v[178:179], v[20:21], v[190:191], v[178:179]
	v_pk_fma_f32 v[180:181], v[18:19], v[190:191], v[180:181]
	v_pk_fma_f32 v[182:183], v[16:17], v[190:191], v[182:183]
	v_pk_fma_f32 v[184:185], v[32:33], v[190:191], v[184:185]
	v_pk_fma_f32 v[186:187], v[76:77], v[190:191], v[186:187]
	v_pk_fma_f32 v[188:189], v[74:75], v[190:191], v[188:189]
	v_pk_fma_f32 v[190:191], v[72:73], v[190:191], v[78:79]
	s_waitcnt vmcnt(63)
	v_lshlrev_b32_e32 v192, 16, v168
	v_and_b32_e32 v193, 0xffff0000, v168
	v_pk_fma_f32 v[168:169], v[36:37], v[192:193], v[170:171]
	v_pk_fma_f32 v[170:171], v[26:27], v[192:193], v[172:173]
	v_pk_fma_f32 v[172:173], v[24:25], v[192:193], v[174:175]
	v_pk_fma_f32 v[174:175], v[22:23], v[192:193], v[176:177]
	v_pk_fma_f32 v[176:177], v[34:35], v[192:193], v[178:179]
	v_pk_fma_f32 v[178:179], v[20:21], v[192:193], v[180:181]
	v_pk_fma_f32 v[180:181], v[18:19], v[192:193], v[182:183]
	v_pk_fma_f32 v[182:183], v[16:17], v[192:193], v[184:185]
	v_pk_fma_f32 v[184:185], v[32:33], v[192:193], v[186:187]
	v_pk_fma_f32 v[186:187], v[76:77], v[192:193], v[188:189]
	v_pk_fma_f32 v[188:189], v[74:75], v[192:193], v[190:191]
	v_pk_fma_f32 v[190:191], v[72:73], v[192:193], v[78:79]
	s_waitcnt vmcnt(63)
	v_lshlrev_b32_e32 v192, 16, v167
	v_and_b32_e32 v193, 0xffff0000, v167
	v_pk_fma_f32 v[168:169], v[28:29], v[192:193], v[168:169]
	v_pk_fma_f32 v[170:171], v[36:37], v[192:193], v[170:171]
	v_pk_fma_f32 v[172:173], v[26:27], v[192:193], v[172:173]
	v_pk_fma_f32 v[174:175], v[24:25], v[192:193], v[174:175]
	v_pk_fma_f32 v[176:177], v[22:23], v[192:193], v[176:177]
	v_pk_fma_f32 v[178:179], v[34:35], v[192:193], v[178:179]
	v_pk_fma_f32 v[180:181], v[20:21], v[192:193], v[180:181]
	v_pk_fma_f32 v[182:183], v[18:19], v[192:193], v[182:183]
	v_pk_fma_f32 v[184:185], v[16:17], v[192:193], v[184:185]
	v_pk_fma_f32 v[186:187], v[32:33], v[192:193], v[186:187]
	v_pk_fma_f32 v[188:189], v[76:77], v[192:193], v[188:189]
	v_pk_fma_f32 v[190:191], v[74:75], v[192:193], v[190:191]
	v_pk_fma_f32 v[192:193], v[72:73], v[192:193], v[78:79]
	s_waitcnt vmcnt(63)
	v_lshlrev_b32_e32 v194, 16, v166
	v_and_b32_e32 v195, 0xffff0000, v166
	v_pk_fma_f32 v[166:167], v[30:31], v[194:195], v[168:169]
	v_pk_fma_f32 v[168:169], v[28:29], v[194:195], v[170:171]
	v_pk_fma_f32 v[170:171], v[36:37], v[194:195], v[172:173]
	v_pk_fma_f32 v[172:173], v[26:27], v[194:195], v[174:175]
	v_pk_fma_f32 v[174:175], v[24:25], v[194:195], v[176:177]
	v_pk_fma_f32 v[176:177], v[22:23], v[194:195], v[178:179]
	v_pk_fma_f32 v[178:179], v[34:35], v[194:195], v[180:181]
	v_pk_fma_f32 v[180:181], v[20:21], v[194:195], v[182:183]
	v_pk_fma_f32 v[182:183], v[18:19], v[194:195], v[184:185]
	v_pk_fma_f32 v[184:185], v[16:17], v[194:195], v[186:187]
	v_pk_fma_f32 v[186:187], v[32:33], v[194:195], v[188:189]
	v_pk_fma_f32 v[188:189], v[76:77], v[194:195], v[190:191]
	v_pk_fma_f32 v[190:191], v[74:75], v[194:195], v[192:193]
	v_pk_fma_f32 v[192:193], v[72:73], v[194:195], v[78:79]
	s_waitcnt vmcnt(63)
	v_lshlrev_b32_e32 v194, 16, v165
	v_and_b32_e32 v195, 0xffff0000, v165
	v_pk_fma_f32 v[166:167], v[40:41], v[194:195], v[166:167]
	v_pk_fma_f32 v[168:169], v[30:31], v[194:195], v[168:169]
	v_pk_fma_f32 v[170:171], v[28:29], v[194:195], v[170:171]
	v_pk_fma_f32 v[172:173], v[36:37], v[194:195], v[172:173]
	v_pk_fma_f32 v[174:175], v[26:27], v[194:195], v[174:175]
	v_pk_fma_f32 v[176:177], v[24:25], v[194:195], v[176:177]
	v_pk_fma_f32 v[178:179], v[22:23], v[194:195], v[178:179]
	v_pk_fma_f32 v[180:181], v[34:35], v[194:195], v[180:181]
	v_pk_fma_f32 v[182:183], v[20:21], v[194:195], v[182:183]
	v_pk_fma_f32 v[184:185], v[18:19], v[194:195], v[184:185]
	v_pk_fma_f32 v[186:187], v[16:17], v[194:195], v[186:187]
	v_pk_fma_f32 v[188:189], v[32:33], v[194:195], v[188:189]
	v_pk_fma_f32 v[190:191], v[76:77], v[194:195], v[190:191]
	v_pk_fma_f32 v[192:193], v[74:75], v[194:195], v[192:193]
	v_pk_fma_f32 v[194:195], v[72:73], v[194:195], v[78:79]
	s_waitcnt vmcnt(63)
	v_lshlrev_b32_e32 v196, 16, v164
	v_and_b32_e32 v197, 0xffff0000, v164
	v_pk_fma_f32 v[164:165], v[38:39], v[196:197], v[166:167]
	v_pk_fma_f32 v[166:167], v[40:41], v[196:197], v[168:169]
	v_pk_fma_f32 v[168:169], v[30:31], v[196:197], v[170:171]
	v_pk_fma_f32 v[170:171], v[28:29], v[196:197], v[172:173]
	v_pk_fma_f32 v[172:173], v[36:37], v[196:197], v[174:175]
	v_pk_fma_f32 v[174:175], v[26:27], v[196:197], v[176:177]
	v_pk_fma_f32 v[176:177], v[24:25], v[196:197], v[178:179]
	v_pk_fma_f32 v[178:179], v[22:23], v[196:197], v[180:181]
	v_pk_fma_f32 v[180:181], v[34:35], v[196:197], v[182:183]
	v_pk_fma_f32 v[182:183], v[20:21], v[196:197], v[184:185]
	v_pk_fma_f32 v[184:185], v[18:19], v[196:197], v[186:187]
	v_pk_fma_f32 v[186:187], v[16:17], v[196:197], v[188:189]
	v_pk_fma_f32 v[188:189], v[32:33], v[196:197], v[190:191]
	v_pk_fma_f32 v[190:191], v[76:77], v[196:197], v[192:193]
	v_pk_fma_f32 v[192:193], v[74:75], v[196:197], v[194:195]
	v_pk_fma_f32 v[194:195], v[72:73], v[196:197], v[78:79]
	s_waitcnt vmcnt(63)
	v_lshlrev_b32_e32 v196, 16, v163
	v_and_b32_e32 v197, 0xffff0000, v163
	v_pk_fma_f32 v[164:165], v[42:43], v[196:197], v[164:165]
	v_pk_fma_f32 v[166:167], v[38:39], v[196:197], v[166:167]
	v_pk_fma_f32 v[168:169], v[40:41], v[196:197], v[168:169]
	v_pk_fma_f32 v[170:171], v[30:31], v[196:197], v[170:171]
	v_pk_fma_f32 v[172:173], v[28:29], v[196:197], v[172:173]
	v_pk_fma_f32 v[174:175], v[36:37], v[196:197], v[174:175]
	v_pk_fma_f32 v[176:177], v[26:27], v[196:197], v[176:177]
	v_pk_fma_f32 v[178:179], v[24:25], v[196:197], v[178:179]
	v_pk_fma_f32 v[180:181], v[22:23], v[196:197], v[180:181]
	v_pk_fma_f32 v[182:183], v[34:35], v[196:197], v[182:183]
	v_pk_fma_f32 v[184:185], v[20:21], v[196:197], v[184:185]
	v_pk_fma_f32 v[186:187], v[18:19], v[196:197], v[186:187]
	v_pk_fma_f32 v[188:189], v[16:17], v[196:197], v[188:189]
	v_pk_fma_f32 v[190:191], v[32:33], v[196:197], v[190:191]
	v_pk_fma_f32 v[192:193], v[76:77], v[196:197], v[192:193]
	v_pk_fma_f32 v[194:195], v[74:75], v[196:197], v[194:195]
	s_waitcnt vmcnt(63)
	v_lshlrev_b32_e32 v196, 16, v162
	v_and_b32_e32 v197, 0xffff0000, v162
	v_pk_fma_f32 v[162:163], v[44:45], v[196:197], v[164:165]
	v_pk_fma_f32 v[164:165], v[42:43], v[196:197], v[166:167]
	v_pk_fma_f32 v[166:167], v[38:39], v[196:197], v[168:169]
	v_pk_fma_f32 v[168:169], v[40:41], v[196:197], v[170:171]
	v_pk_fma_f32 v[170:171], v[30:31], v[196:197], v[172:173]
	v_pk_fma_f32 v[172:173], v[28:29], v[196:197], v[174:175]
	v_pk_fma_f32 v[174:175], v[36:37], v[196:197], v[176:177]
	v_pk_fma_f32 v[176:177], v[26:27], v[196:197], v[178:179]
	v_pk_fma_f32 v[178:179], v[24:25], v[196:197], v[180:181]
	v_pk_fma_f32 v[180:181], v[22:23], v[196:197], v[182:183]
	v_pk_fma_f32 v[182:183], v[34:35], v[196:197], v[184:185]
	v_pk_fma_f32 v[184:185], v[20:21], v[196:197], v[186:187]
	v_pk_fma_f32 v[186:187], v[18:19], v[196:197], v[188:189]
	v_pk_fma_f32 v[188:189], v[16:17], v[196:197], v[190:191]
	v_pk_fma_f32 v[190:191], v[32:33], v[196:197], v[192:193]
	v_pk_fma_f32 v[192:193], v[76:77], v[196:197], v[194:195]
	s_waitcnt vmcnt(63)
	v_lshlrev_b32_e32 v194, 16, v161
	v_and_b32_e32 v195, 0xffff0000, v161
	v_pk_fma_f32 v[162:163], v[46:47], v[194:195], v[162:163]
	v_pk_fma_f32 v[164:165], v[44:45], v[194:195], v[164:165]
	v_pk_fma_f32 v[166:167], v[42:43], v[194:195], v[166:167]
	v_pk_fma_f32 v[168:169], v[38:39], v[194:195], v[168:169]
	v_pk_fma_f32 v[170:171], v[40:41], v[194:195], v[170:171]
	v_pk_fma_f32 v[172:173], v[30:31], v[194:195], v[172:173]
	v_pk_fma_f32 v[174:175], v[28:29], v[194:195], v[174:175]
	v_pk_fma_f32 v[176:177], v[36:37], v[194:195], v[176:177]
	v_pk_fma_f32 v[178:179], v[26:27], v[194:195], v[178:179]
	v_pk_fma_f32 v[180:181], v[24:25], v[194:195], v[180:181]
	v_pk_fma_f32 v[182:183], v[22:23], v[194:195], v[182:183]
	v_pk_fma_f32 v[184:185], v[34:35], v[194:195], v[184:185]
	v_pk_fma_f32 v[186:187], v[20:21], v[194:195], v[186:187]
	v_pk_fma_f32 v[188:189], v[18:19], v[194:195], v[188:189]
	v_pk_fma_f32 v[190:191], v[16:17], v[194:195], v[190:191]
	v_pk_fma_f32 v[192:193], v[32:33], v[194:195], v[192:193]
	s_waitcnt vmcnt(63)
	v_lshlrev_b32_e32 v194, 16, v160
	v_and_b32_e32 v195, 0xffff0000, v160
	v_pk_fma_f32 v[160:161], v[64:65], v[194:195], v[162:163]
	v_pk_fma_f32 v[162:163], v[46:47], v[194:195], v[164:165]
	v_pk_fma_f32 v[164:165], v[44:45], v[194:195], v[166:167]
	v_pk_fma_f32 v[166:167], v[42:43], v[194:195], v[168:169]
	v_pk_fma_f32 v[168:169], v[38:39], v[194:195], v[170:171]
	v_pk_fma_f32 v[170:171], v[40:41], v[194:195], v[172:173]
	v_pk_fma_f32 v[172:173], v[30:31], v[194:195], v[174:175]
	v_pk_fma_f32 v[174:175], v[28:29], v[194:195], v[176:177]
	v_pk_fma_f32 v[176:177], v[36:37], v[194:195], v[178:179]
	v_pk_fma_f32 v[178:179], v[26:27], v[194:195], v[180:181]
	v_pk_fma_f32 v[180:181], v[24:25], v[194:195], v[182:183]
	v_pk_fma_f32 v[182:183], v[22:23], v[194:195], v[184:185]
	v_pk_fma_f32 v[184:185], v[34:35], v[194:195], v[186:187]
	v_pk_fma_f32 v[186:187], v[20:21], v[194:195], v[188:189]
	v_pk_fma_f32 v[188:189], v[18:19], v[194:195], v[190:191]
	v_pk_fma_f32 v[190:191], v[16:17], v[194:195], v[192:193]
	s_waitcnt vmcnt(63)
	v_lshlrev_b32_e32 v192, 16, v159
	v_and_b32_e32 v193, 0xffff0000, v159
	v_pk_fma_f32 v[160:161], v[48:49], v[192:193], v[160:161]
	v_pk_fma_f32 v[162:163], v[64:65], v[192:193], v[162:163]
	v_pk_fma_f32 v[164:165], v[46:47], v[192:193], v[164:165]
	v_pk_fma_f32 v[166:167], v[44:45], v[192:193], v[166:167]
	v_pk_fma_f32 v[168:169], v[42:43], v[192:193], v[168:169]
	v_pk_fma_f32 v[170:171], v[38:39], v[192:193], v[170:171]
	v_pk_fma_f32 v[172:173], v[40:41], v[192:193], v[172:173]
	v_pk_fma_f32 v[174:175], v[30:31], v[192:193], v[174:175]
	v_pk_fma_f32 v[176:177], v[28:29], v[192:193], v[176:177]
	v_pk_fma_f32 v[178:179], v[36:37], v[192:193], v[178:179]
	v_pk_fma_f32 v[180:181], v[26:27], v[192:193], v[180:181]
	v_pk_fma_f32 v[182:183], v[24:25], v[192:193], v[182:183]
	v_pk_fma_f32 v[184:185], v[22:23], v[192:193], v[184:185]
	v_pk_fma_f32 v[186:187], v[34:35], v[192:193], v[186:187]
	v_pk_fma_f32 v[188:189], v[20:21], v[192:193], v[188:189]
	v_pk_fma_f32 v[190:191], v[18:19], v[192:193], v[190:191]
	s_waitcnt vmcnt(63)
	v_lshlrev_b32_e32 v192, 16, v158
	v_and_b32_e32 v193, 0xffff0000, v158
	v_pk_fma_f32 v[158:159], v[50:51], v[192:193], v[160:161]
	v_pk_fma_f32 v[160:161], v[48:49], v[192:193], v[162:163]
	v_pk_fma_f32 v[162:163], v[64:65], v[192:193], v[164:165]
	v_pk_fma_f32 v[164:165], v[46:47], v[192:193], v[166:167]
	v_pk_fma_f32 v[166:167], v[44:45], v[192:193], v[168:169]
	v_pk_fma_f32 v[168:169], v[42:43], v[192:193], v[170:171]
	v_pk_fma_f32 v[170:171], v[38:39], v[192:193], v[172:173]
	v_pk_fma_f32 v[172:173], v[40:41], v[192:193], v[174:175]
	v_pk_fma_f32 v[174:175], v[30:31], v[192:193], v[176:177]
	v_pk_fma_f32 v[176:177], v[28:29], v[192:193], v[178:179]
	v_pk_fma_f32 v[178:179], v[36:37], v[192:193], v[180:181]
	v_pk_fma_f32 v[180:181], v[26:27], v[192:193], v[182:183]
	v_pk_fma_f32 v[182:183], v[24:25], v[192:193], v[184:185]
	v_pk_fma_f32 v[184:185], v[22:23], v[192:193], v[186:187]
	v_pk_fma_f32 v[186:187], v[34:35], v[192:193], v[188:189]
	v_pk_fma_f32 v[188:189], v[20:21], v[192:193], v[190:191]
	s_waitcnt vmcnt(63)
	v_lshlrev_b32_e32 v190, 16, v157
	v_and_b32_e32 v191, 0xffff0000, v157
	v_pk_fma_f32 v[158:159], v[52:53], v[190:191], v[158:159]
	v_pk_fma_f32 v[160:161], v[50:51], v[190:191], v[160:161]
	v_pk_fma_f32 v[162:163], v[48:49], v[190:191], v[162:163]
	v_pk_fma_f32 v[164:165], v[64:65], v[190:191], v[164:165]
	v_pk_fma_f32 v[166:167], v[46:47], v[190:191], v[166:167]
	v_pk_fma_f32 v[168:169], v[44:45], v[190:191], v[168:169]
	v_pk_fma_f32 v[170:171], v[42:43], v[190:191], v[170:171]
	v_pk_fma_f32 v[172:173], v[38:39], v[190:191], v[172:173]
	v_pk_fma_f32 v[174:175], v[40:41], v[190:191], v[174:175]
	v_pk_fma_f32 v[176:177], v[30:31], v[190:191], v[176:177]
	v_pk_fma_f32 v[178:179], v[28:29], v[190:191], v[178:179]
	v_pk_fma_f32 v[180:181], v[36:37], v[190:191], v[180:181]
	v_pk_fma_f32 v[182:183], v[26:27], v[190:191], v[182:183]
	v_pk_fma_f32 v[184:185], v[24:25], v[190:191], v[184:185]
	v_pk_fma_f32 v[186:187], v[22:23], v[190:191], v[186:187]
	v_pk_fma_f32 v[188:189], v[34:35], v[190:191], v[188:189]
	s_waitcnt vmcnt(63)
	v_lshlrev_b32_e32 v190, 16, v156
	v_and_b32_e32 v191, 0xffff0000, v156
	v_pk_fma_f32 v[156:157], v[66:67], v[190:191], v[158:159]
	v_pk_fma_f32 v[158:159], v[52:53], v[190:191], v[160:161]
	v_pk_fma_f32 v[160:161], v[50:51], v[190:191], v[162:163]
	v_pk_fma_f32 v[162:163], v[48:49], v[190:191], v[164:165]
	v_pk_fma_f32 v[164:165], v[64:65], v[190:191], v[166:167]
	v_pk_fma_f32 v[166:167], v[46:47], v[190:191], v[168:169]
	v_pk_fma_f32 v[168:169], v[44:45], v[190:191], v[170:171]
	v_pk_fma_f32 v[170:171], v[42:43], v[190:191], v[172:173]
	v_pk_fma_f32 v[172:173], v[38:39], v[190:191], v[174:175]
	v_pk_fma_f32 v[174:175], v[40:41], v[190:191], v[176:177]
	v_pk_fma_f32 v[176:177], v[30:31], v[190:191], v[178:179]
	v_pk_fma_f32 v[178:179], v[28:29], v[190:191], v[180:181]
	v_pk_fma_f32 v[180:181], v[36:37], v[190:191], v[182:183]
	v_pk_fma_f32 v[182:183], v[26:27], v[190:191], v[184:185]
	v_pk_fma_f32 v[184:185], v[24:25], v[190:191], v[186:187]
	v_pk_fma_f32 v[186:187], v[22:23], v[190:191], v[188:189]
	s_waitcnt vmcnt(63)
	v_lshlrev_b32_e32 v188, 16, v155
	v_and_b32_e32 v189, 0xffff0000, v155
	v_pk_fma_f32 v[156:157], v[54:55], v[188:189], v[156:157]
	v_pk_fma_f32 v[158:159], v[66:67], v[188:189], v[158:159]
	v_pk_fma_f32 v[160:161], v[52:53], v[188:189], v[160:161]
	v_pk_fma_f32 v[162:163], v[50:51], v[188:189], v[162:163]
	v_pk_fma_f32 v[164:165], v[48:49], v[188:189], v[164:165]
	v_pk_fma_f32 v[166:167], v[64:65], v[188:189], v[166:167]
	v_pk_fma_f32 v[168:169], v[46:47], v[188:189], v[168:169]
	v_pk_fma_f32 v[170:171], v[44:45], v[188:189], v[170:171]
	v_pk_fma_f32 v[172:173], v[42:43], v[188:189], v[172:173]
	v_pk_fma_f32 v[174:175], v[38:39], v[188:189], v[174:175]
	v_pk_fma_f32 v[176:177], v[40:41], v[188:189], v[176:177]
	v_pk_fma_f32 v[178:179], v[30:31], v[188:189], v[178:179]
	v_pk_fma_f32 v[180:181], v[28:29], v[188:189], v[180:181]
	v_pk_fma_f32 v[182:183], v[36:37], v[188:189], v[182:183]
	v_pk_fma_f32 v[184:185], v[26:27], v[188:189], v[184:185]
	v_pk_fma_f32 v[186:187], v[24:25], v[188:189], v[186:187]
	s_waitcnt vmcnt(63)
	v_lshlrev_b32_e32 v188, 16, v154
	v_and_b32_e32 v189, 0xffff0000, v154
	v_pk_fma_f32 v[154:155], v[56:57], v[188:189], v[156:157]
	v_pk_fma_f32 v[156:157], v[54:55], v[188:189], v[158:159]
	v_pk_fma_f32 v[158:159], v[66:67], v[188:189], v[160:161]
	v_pk_fma_f32 v[160:161], v[52:53], v[188:189], v[162:163]
	v_pk_fma_f32 v[162:163], v[50:51], v[188:189], v[164:165]
	v_pk_fma_f32 v[164:165], v[48:49], v[188:189], v[166:167]
	v_pk_fma_f32 v[166:167], v[64:65], v[188:189], v[168:169]
	v_pk_fma_f32 v[168:169], v[46:47], v[188:189], v[170:171]
	v_pk_fma_f32 v[170:171], v[44:45], v[188:189], v[172:173]
	v_pk_fma_f32 v[172:173], v[42:43], v[188:189], v[174:175]
	v_pk_fma_f32 v[174:175], v[38:39], v[188:189], v[176:177]
	v_pk_fma_f32 v[176:177], v[40:41], v[188:189], v[178:179]
	v_pk_fma_f32 v[178:179], v[30:31], v[188:189], v[180:181]
	v_pk_fma_f32 v[180:181], v[28:29], v[188:189], v[182:183]
	v_pk_fma_f32 v[182:183], v[36:37], v[188:189], v[184:185]
	v_pk_fma_f32 v[184:185], v[26:27], v[188:189], v[186:187]
	s_waitcnt vmcnt(63)
	v_lshlrev_b32_e32 v186, 16, v153
	v_and_b32_e32 v187, 0xffff0000, v153
	v_pk_fma_f32 v[154:155], v[58:59], v[186:187], v[154:155]
	v_pk_fma_f32 v[156:157], v[56:57], v[186:187], v[156:157]
	v_pk_fma_f32 v[158:159], v[54:55], v[186:187], v[158:159]
	v_pk_fma_f32 v[160:161], v[66:67], v[186:187], v[160:161]
	v_pk_fma_f32 v[162:163], v[52:53], v[186:187], v[162:163]
	v_pk_fma_f32 v[164:165], v[50:51], v[186:187], v[164:165]
	v_pk_fma_f32 v[166:167], v[48:49], v[186:187], v[166:167]
	v_pk_fma_f32 v[168:169], v[64:65], v[186:187], v[168:169]
	v_pk_fma_f32 v[170:171], v[46:47], v[186:187], v[170:171]
	v_pk_fma_f32 v[172:173], v[44:45], v[186:187], v[172:173]
	v_pk_fma_f32 v[174:175], v[42:43], v[186:187], v[174:175]
	v_pk_fma_f32 v[176:177], v[38:39], v[186:187], v[176:177]
	v_pk_fma_f32 v[178:179], v[40:41], v[186:187], v[178:179]
	v_pk_fma_f32 v[180:181], v[30:31], v[186:187], v[180:181]
	v_pk_fma_f32 v[182:183], v[28:29], v[186:187], v[182:183]
	v_pk_fma_f32 v[184:185], v[36:37], v[186:187], v[184:185]
	s_waitcnt vmcnt(63)
	v_lshlrev_b32_e32 v186, 16, v152
	v_and_b32_e32 v187, 0xffff0000, v152
	v_pk_fma_f32 v[152:153], v[68:69], v[186:187], v[154:155]
	v_pk_fma_f32 v[154:155], v[58:59], v[186:187], v[156:157]
	v_pk_fma_f32 v[156:157], v[56:57], v[186:187], v[158:159]
	v_pk_fma_f32 v[158:159], v[54:55], v[186:187], v[160:161]
	v_pk_fma_f32 v[160:161], v[66:67], v[186:187], v[162:163]
	v_pk_fma_f32 v[162:163], v[52:53], v[186:187], v[164:165]
	v_pk_fma_f32 v[164:165], v[50:51], v[186:187], v[166:167]
	v_pk_fma_f32 v[166:167], v[48:49], v[186:187], v[168:169]
	v_pk_fma_f32 v[168:169], v[64:65], v[186:187], v[170:171]
	v_pk_fma_f32 v[170:171], v[46:47], v[186:187], v[172:173]
	v_pk_fma_f32 v[172:173], v[44:45], v[186:187], v[174:175]
	v_pk_fma_f32 v[174:175], v[42:43], v[186:187], v[176:177]
	v_pk_fma_f32 v[176:177], v[38:39], v[186:187], v[178:179]
	v_pk_fma_f32 v[178:179], v[40:41], v[186:187], v[180:181]
	v_pk_fma_f32 v[180:181], v[30:31], v[186:187], v[182:183]
	v_pk_fma_f32 v[182:183], v[28:29], v[186:187], v[184:185]
	s_waitcnt vmcnt(63)
	v_lshlrev_b32_e32 v184, 16, v151
	v_and_b32_e32 v185, 0xffff0000, v151
	v_pk_fma_f32 v[152:153], v[60:61], v[184:185], v[152:153]
	v_pk_fma_f32 v[154:155], v[68:69], v[184:185], v[154:155]
	v_pk_fma_f32 v[156:157], v[58:59], v[184:185], v[156:157]
	v_pk_fma_f32 v[158:159], v[56:57], v[184:185], v[158:159]
	v_pk_fma_f32 v[160:161], v[54:55], v[184:185], v[160:161]
	v_pk_fma_f32 v[162:163], v[66:67], v[184:185], v[162:163]
	v_pk_fma_f32 v[164:165], v[52:53], v[184:185], v[164:165]
	v_pk_fma_f32 v[166:167], v[50:51], v[184:185], v[166:167]
	v_pk_fma_f32 v[168:169], v[48:49], v[184:185], v[168:169]
	v_pk_fma_f32 v[170:171], v[64:65], v[184:185], v[170:171]
	v_pk_fma_f32 v[172:173], v[46:47], v[184:185], v[172:173]
	v_pk_fma_f32 v[174:175], v[44:45], v[184:185], v[174:175]
	v_pk_fma_f32 v[176:177], v[42:43], v[184:185], v[176:177]
	v_pk_fma_f32 v[178:179], v[38:39], v[184:185], v[178:179]
	v_pk_fma_f32 v[180:181], v[40:41], v[184:185], v[180:181]
	v_pk_fma_f32 v[182:183], v[30:31], v[184:185], v[182:183]
	s_waitcnt vmcnt(62)
	v_lshlrev_b32_e32 v184, 16, v150
	v_and_b32_e32 v185, 0xffff0000, v150
	v_pk_fma_f32 v[150:151], v[62:63], v[184:185], v[152:153]
	v_pk_fma_f32 v[152:153], v[60:61], v[184:185], v[154:155]
	v_pk_fma_f32 v[154:155], v[68:69], v[184:185], v[156:157]
	v_pk_fma_f32 v[156:157], v[58:59], v[184:185], v[158:159]
	v_pk_fma_f32 v[158:159], v[56:57], v[184:185], v[160:161]
	v_pk_fma_f32 v[160:161], v[54:55], v[184:185], v[162:163]
	v_pk_fma_f32 v[162:163], v[66:67], v[184:185], v[164:165]
	v_pk_fma_f32 v[164:165], v[52:53], v[184:185], v[166:167]
	v_pk_fma_f32 v[166:167], v[50:51], v[184:185], v[168:169]
	v_pk_fma_f32 v[168:169], v[48:49], v[184:185], v[170:171]
	v_pk_fma_f32 v[170:171], v[64:65], v[184:185], v[172:173]
	v_pk_fma_f32 v[172:173], v[46:47], v[184:185], v[174:175]
	v_pk_fma_f32 v[174:175], v[44:45], v[184:185], v[176:177]
	v_pk_fma_f32 v[176:177], v[42:43], v[184:185], v[178:179]
	v_pk_fma_f32 v[178:179], v[38:39], v[184:185], v[180:181]
	v_pk_fma_f32 v[180:181], v[40:41], v[184:185], v[182:183]
	s_waitcnt vmcnt(61)
	v_lshlrev_b32_e32 v182, 16, v149
	v_and_b32_e32 v183, 0xffff0000, v149
	v_pk_fma_f32 v[150:151], v[70:71], v[182:183], v[150:151]
	v_pk_fma_f32 v[152:153], v[62:63], v[182:183], v[152:153]
	v_pk_fma_f32 v[154:155], v[60:61], v[182:183], v[154:155]
	v_pk_fma_f32 v[156:157], v[68:69], v[182:183], v[156:157]
	v_pk_fma_f32 v[158:159], v[58:59], v[182:183], v[158:159]
	v_pk_fma_f32 v[160:161], v[56:57], v[182:183], v[160:161]
	v_pk_fma_f32 v[162:163], v[54:55], v[182:183], v[162:163]
	v_pk_fma_f32 v[164:165], v[66:67], v[182:183], v[164:165]
	v_pk_fma_f32 v[166:167], v[52:53], v[182:183], v[166:167]
	v_pk_fma_f32 v[168:169], v[50:51], v[182:183], v[168:169]
	v_pk_fma_f32 v[170:171], v[48:49], v[182:183], v[170:171]
	v_pk_fma_f32 v[172:173], v[64:65], v[182:183], v[172:173]
	v_pk_fma_f32 v[174:175], v[46:47], v[182:183], v[174:175]
	v_pk_fma_f32 v[176:177], v[44:45], v[182:183], v[176:177]
	v_pk_fma_f32 v[178:179], v[42:43], v[182:183], v[178:179]
	v_pk_fma_f32 v[180:181], v[38:39], v[182:183], v[180:181]
	s_waitcnt vmcnt(60)
	v_lshlrev_b32_e32 v182, 16, v148
	v_and_b32_e32 v183, 0xffff0000, v148
	v_pk_fma_f32 v[148:149], v[70:71], v[182:183], v[152:153]
	v_pk_fma_f32 v[152:153], v[62:63], v[182:183], v[154:155]
	v_pk_fma_f32 v[154:155], v[60:61], v[182:183], v[156:157]
	v_pk_fma_f32 v[156:157], v[68:69], v[182:183], v[158:159]
	v_pk_fma_f32 v[158:159], v[58:59], v[182:183], v[160:161]
	v_pk_fma_f32 v[160:161], v[56:57], v[182:183], v[162:163]
	v_pk_fma_f32 v[162:163], v[54:55], v[182:183], v[164:165]
	v_pk_fma_f32 v[164:165], v[66:67], v[182:183], v[166:167]
	v_pk_fma_f32 v[166:167], v[52:53], v[182:183], v[168:169]
	v_pk_fma_f32 v[168:169], v[50:51], v[182:183], v[170:171]
	v_pk_fma_f32 v[170:171], v[48:49], v[182:183], v[172:173]
	v_pk_fma_f32 v[172:173], v[64:65], v[182:183], v[174:175]
	v_pk_fma_f32 v[174:175], v[46:47], v[182:183], v[176:177]
	v_pk_fma_f32 v[176:177], v[44:45], v[182:183], v[178:179]
	v_pk_fma_f32 v[178:179], v[42:43], v[182:183], v[180:181]
	s_waitcnt vmcnt(59)
	v_lshlrev_b32_e32 v180, 16, v147
	v_and_b32_e32 v181, 0xffff0000, v147
	v_pk_fma_f32 v[152:153], v[70:71], v[180:181], v[152:153]
	v_pk_fma_f32 v[154:155], v[62:63], v[180:181], v[154:155]
	v_pk_fma_f32 v[156:157], v[60:61], v[180:181], v[156:157]
	v_pk_fma_f32 v[158:159], v[68:69], v[180:181], v[158:159]
	v_pk_fma_f32 v[160:161], v[58:59], v[180:181], v[160:161]
	v_pk_fma_f32 v[162:163], v[56:57], v[180:181], v[162:163]
	v_pk_fma_f32 v[164:165], v[54:55], v[180:181], v[164:165]
	v_pk_fma_f32 v[166:167], v[66:67], v[180:181], v[166:167]
	v_pk_fma_f32 v[168:169], v[52:53], v[180:181], v[168:169]
	v_pk_fma_f32 v[170:171], v[50:51], v[180:181], v[170:171]
	v_pk_fma_f32 v[172:173], v[48:49], v[180:181], v[172:173]
	v_pk_fma_f32 v[174:175], v[64:65], v[180:181], v[174:175]
	v_pk_fma_f32 v[176:177], v[46:47], v[180:181], v[176:177]
	v_pk_fma_f32 v[178:179], v[44:45], v[180:181], v[178:179]
	s_waitcnt vmcnt(58)
	v_lshlrev_b32_e32 v180, 16, v146
	v_and_b32_e32 v181, 0xffff0000, v146
	v_pk_fma_f32 v[146:147], v[70:71], v[180:181], v[154:155]
	v_pk_fma_f32 v[154:155], v[62:63], v[180:181], v[156:157]
	v_pk_fma_f32 v[156:157], v[60:61], v[180:181], v[158:159]
	v_pk_fma_f32 v[158:159], v[68:69], v[180:181], v[160:161]
	v_pk_fma_f32 v[160:161], v[58:59], v[180:181], v[162:163]
	v_pk_fma_f32 v[162:163], v[56:57], v[180:181], v[164:165]
	v_pk_fma_f32 v[164:165], v[54:55], v[180:181], v[166:167]
	v_pk_fma_f32 v[166:167], v[66:67], v[180:181], v[168:169]
	v_pk_fma_f32 v[168:169], v[52:53], v[180:181], v[170:171]
	v_pk_fma_f32 v[170:171], v[50:51], v[180:181], v[172:173]
	v_pk_fma_f32 v[172:173], v[48:49], v[180:181], v[174:175]
	v_pk_fma_f32 v[174:175], v[64:65], v[180:181], v[176:177]
	v_pk_fma_f32 v[176:177], v[46:47], v[180:181], v[178:179]
	s_waitcnt vmcnt(57)
	v_lshlrev_b32_e32 v178, 16, v145
	v_and_b32_e32 v179, 0xffff0000, v145
	v_pk_fma_f32 v[154:155], v[70:71], v[178:179], v[154:155]
	v_pk_fma_f32 v[156:157], v[62:63], v[178:179], v[156:157]
	v_pk_fma_f32 v[158:159], v[60:61], v[178:179], v[158:159]
	v_pk_fma_f32 v[160:161], v[68:69], v[178:179], v[160:161]
	v_pk_fma_f32 v[162:163], v[58:59], v[178:179], v[162:163]
	v_pk_fma_f32 v[164:165], v[56:57], v[178:179], v[164:165]
	v_pk_fma_f32 v[166:167], v[54:55], v[178:179], v[166:167]
	v_pk_fma_f32 v[168:169], v[66:67], v[178:179], v[168:169]
	v_pk_fma_f32 v[170:171], v[52:53], v[178:179], v[170:171]
	v_pk_fma_f32 v[172:173], v[50:51], v[178:179], v[172:173]
	v_pk_fma_f32 v[174:175], v[48:49], v[178:179], v[174:175]
	v_pk_fma_f32 v[176:177], v[64:65], v[178:179], v[176:177]
	s_waitcnt vmcnt(56)
	v_lshlrev_b32_e32 v178, 16, v144
	v_and_b32_e32 v179, 0xffff0000, v144
	v_pk_fma_f32 v[144:145], v[70:71], v[178:179], v[156:157]
	v_pk_fma_f32 v[156:157], v[62:63], v[178:179], v[158:159]
	v_pk_fma_f32 v[158:159], v[60:61], v[178:179], v[160:161]
	v_pk_fma_f32 v[160:161], v[68:69], v[178:179], v[162:163]
	v_pk_fma_f32 v[162:163], v[58:59], v[178:179], v[164:165]
	v_pk_fma_f32 v[164:165], v[56:57], v[178:179], v[166:167]
	v_pk_fma_f32 v[166:167], v[54:55], v[178:179], v[168:169]
	v_pk_fma_f32 v[168:169], v[66:67], v[178:179], v[170:171]
	v_pk_fma_f32 v[170:171], v[52:53], v[178:179], v[172:173]
	v_pk_fma_f32 v[172:173], v[50:51], v[178:179], v[174:175]
	v_pk_fma_f32 v[174:175], v[48:49], v[178:179], v[176:177]
	s_waitcnt vmcnt(55)
	v_lshlrev_b32_e32 v176, 16, v143
	v_and_b32_e32 v177, 0xffff0000, v143
	v_pk_fma_f32 v[156:157], v[70:71], v[176:177], v[156:157]
	v_pk_fma_f32 v[158:159], v[62:63], v[176:177], v[158:159]
	v_pk_fma_f32 v[160:161], v[60:61], v[176:177], v[160:161]
	v_pk_fma_f32 v[162:163], v[68:69], v[176:177], v[162:163]
	v_pk_fma_f32 v[164:165], v[58:59], v[176:177], v[164:165]
	v_pk_fma_f32 v[166:167], v[56:57], v[176:177], v[166:167]
	v_pk_fma_f32 v[168:169], v[54:55], v[176:177], v[168:169]
	v_pk_fma_f32 v[170:171], v[66:67], v[176:177], v[170:171]
	v_pk_fma_f32 v[172:173], v[52:53], v[176:177], v[172:173]
	v_pk_fma_f32 v[174:175], v[50:51], v[176:177], v[174:175]
	s_waitcnt vmcnt(54)
	v_lshlrev_b32_e32 v176, 16, v142
	v_and_b32_e32 v177, 0xffff0000, v142
	v_pk_fma_f32 v[142:143], v[70:71], v[176:177], v[158:159]
	v_pk_fma_f32 v[158:159], v[62:63], v[176:177], v[160:161]
	v_pk_fma_f32 v[160:161], v[60:61], v[176:177], v[162:163]
	v_pk_fma_f32 v[162:163], v[68:69], v[176:177], v[164:165]
	v_pk_fma_f32 v[164:165], v[58:59], v[176:177], v[166:167]
	v_pk_fma_f32 v[166:167], v[56:57], v[176:177], v[168:169]
	v_pk_fma_f32 v[168:169], v[54:55], v[176:177], v[170:171]
	v_pk_fma_f32 v[170:171], v[66:67], v[176:177], v[172:173]
	v_pk_fma_f32 v[172:173], v[52:53], v[176:177], v[174:175]
	s_waitcnt vmcnt(53)
	v_lshlrev_b32_e32 v174, 16, v141
	v_and_b32_e32 v175, 0xffff0000, v141
	v_pk_fma_f32 v[158:159], v[70:71], v[174:175], v[158:159]
	v_pk_fma_f32 v[160:161], v[62:63], v[174:175], v[160:161]
	v_pk_fma_f32 v[162:163], v[60:61], v[174:175], v[162:163]
	v_pk_fma_f32 v[164:165], v[68:69], v[174:175], v[164:165]
	v_pk_fma_f32 v[166:167], v[58:59], v[174:175], v[166:167]
	v_pk_fma_f32 v[168:169], v[56:57], v[174:175], v[168:169]
	v_pk_fma_f32 v[170:171], v[54:55], v[174:175], v[170:171]
	v_pk_fma_f32 v[172:173], v[66:67], v[174:175], v[172:173]
	s_waitcnt vmcnt(52)
	v_lshlrev_b32_e32 v174, 16, v139
	v_and_b32_e32 v175, 0xffff0000, v139
	v_pk_fma_f32 v[160:161], v[70:71], v[174:175], v[160:161]
	v_pk_fma_f32 v[162:163], v[62:63], v[174:175], v[162:163]
	v_pk_fma_f32 v[164:165], v[60:61], v[174:175], v[164:165]
	v_pk_fma_f32 v[166:167], v[68:69], v[174:175], v[166:167]
	v_pk_fma_f32 v[168:169], v[58:59], v[174:175], v[168:169]
	v_pk_fma_f32 v[170:171], v[56:57], v[174:175], v[170:171]
	v_pk_fma_f32 v[172:173], v[54:55], v[174:175], v[172:173]
	s_waitcnt vmcnt(51)
	v_lshlrev_b32_e32 v174, 16, v140
	v_and_b32_e32 v175, 0xffff0000, v140
	v_pk_fma_f32 v[140:141], v[70:71], v[174:175], v[162:163]
	v_pk_fma_f32 v[162:163], v[62:63], v[174:175], v[164:165]
	v_pk_fma_f32 v[164:165], v[60:61], v[174:175], v[166:167]
	v_pk_fma_f32 v[166:167], v[68:69], v[174:175], v[168:169]
	v_pk_fma_f32 v[168:169], v[58:59], v[174:175], v[170:171]
	v_pk_fma_f32 v[170:171], v[56:57], v[174:175], v[172:173]
	s_waitcnt vmcnt(50)
	v_lshlrev_b32_e32 v172, 16, v138
	v_and_b32_e32 v173, 0xffff0000, v138
	v_pk_fma_f32 v[138:139], v[70:71], v[172:173], v[162:163]
	v_pk_fma_f32 v[162:163], v[62:63], v[172:173], v[164:165]
	v_pk_fma_f32 v[164:165], v[60:61], v[172:173], v[166:167]
	v_pk_fma_f32 v[166:167], v[68:69], v[172:173], v[168:169]
	v_pk_fma_f32 v[168:169], v[58:59], v[172:173], v[170:171]
	s_waitcnt vmcnt(49)
	v_lshlrev_b32_e32 v170, 16, v137
	v_and_b32_e32 v171, 0xffff0000, v137
	v_pk_fma_f32 v[162:163], v[70:71], v[170:171], v[162:163]
	v_pk_fma_f32 v[164:165], v[62:63], v[170:171], v[164:165]
	v_pk_fma_f32 v[166:167], v[60:61], v[170:171], v[166:167]
	v_pk_fma_f32 v[168:169], v[68:69], v[170:171], v[168:169]
	s_waitcnt vmcnt(48)
	v_lshlrev_b32_e32 v170, 16, v136
	v_and_b32_e32 v171, 0xffff0000, v136
	v_pk_fma_f32 v[136:137], v[70:71], v[170:171], v[164:165]
	v_pk_fma_f32 v[164:165], v[62:63], v[170:171], v[166:167]
	v_pk_fma_f32 v[166:167], v[60:61], v[170:171], v[168:169]
	s_waitcnt vmcnt(47)
	v_lshlrev_b32_e32 v168, 16, v135
	v_and_b32_e32 v169, 0xffff0000, v135
	v_pk_fma_f32 v[164:165], v[70:71], v[168:169], v[164:165]
	v_pk_fma_f32 v[166:167], v[62:63], v[168:169], v[166:167]
	s_waitcnt vmcnt(46)
	s_branch .Lconv_pf_join
